# K-loop LDS-DMA loads use SGPR-base + 32-bit VGPR offset form (drops 16 64-bit VALU adds per iteration)
# speedup vs baseline: 1.0000x; 1.0000x over previous
.LBB0_324:
	s_add_i32 vcc_lo, s66, 2
	s_add_u32 s34, s8, 0xfff00080
	s_addc_u32 s35, s9, -1
	s_add_i32 s89, 0, 0x10000
	s_cmp_eq_u32 s59, s66
	s_cselect_b32 s95, s65, s35
	s_cselect_b32 s94, s64, s34
	v_add_u32_e32 v0, s89, v217
	s_cselect_b32 s67, s53, s80
	s_cselect_b32 s66, s52, s70
	s_add_i32 vcc_hi, 0, 0x14000
	ds_read_b128 v[132:135], v0
	ds_read_b128 v[136:139], v0 offset:1024
	ds_read_b128 v[140:143], v0 offset:2048
	ds_read_b128 v[144:147], v0 offset:3072
	v_add_u32_e32 v0, vcc_hi, v217
	ds_read_b128 v[148:151], v0
	ds_read_b128 v[152:155], v0 offset:1024
	ds_read_b128 v[156:159], v0 offset:2048
	ds_read_b128 v[160:163], v0 offset:3072
	v_add_u32_e32 v0, 0, v216
	s_add_i32 m0, s29, 0xc000
	ds_read_b128 v[164:167], v0
	ds_read_b128 v[168:171], v0 offset:1024
	ds_read_b128 v[172:175], v0 offset:2048
	ds_read_b128 v[176:179], v0 offset:3072
	ds_read_b128 v[180:183], v0 offset:4096
	ds_read_b128 v[184:187], v0 offset:5120
	ds_read_b128 v[188:191], v0 offset:6144
	ds_read_b128 v[250:253], v0 offset:7168
	global_load_lds_dwordx4 v204, s[8:9]
	s_add_i32 m0, s29, 0xe000
	s_nop 0
	global_load_lds_dwordx4 v206, s[8:9]
	s_waitcnt vmcnt(8)
	s_waitcnt lgkmcnt(0)
	s_barrier
	s_setprio 1
	s_waitcnt lgkmcnt(0)
	v_mfma_f32_16x16x32_bf16 v[128:131], v[132:135], v[164:167], v[128:131]
	v_mfma_f32_16x16x32_bf16 v[112:115], v[140:143], v[164:167], v[112:115]
	v_mfma_f32_16x16x32_bf16 v[120:123], v[132:135], v[172:175], v[120:123]
	v_mfma_f32_16x16x32_bf16 v[96:99], v[140:143], v[172:175], v[96:99]
	v_mfma_f32_16x16x32_bf16 v[104:107], v[132:135], v[180:183], v[104:107]
	v_mfma_f32_16x16x32_bf16 v[88:91], v[140:143], v[180:183], v[88:91]
	v_mfma_f32_16x16x32_bf16 v[84:87], v[132:135], v[188:191], v[84:87]
	v_mfma_f32_16x16x32_bf16 v[72:75], v[140:143], v[188:191], v[72:75]
	v_mfma_f32_16x16x32_bf16 v[128:131], v[136:139], v[168:171], v[128:131]
	v_mfma_f32_16x16x32_bf16 v[112:115], v[144:147], v[168:171], v[112:115]
	v_mfma_f32_16x16x32_bf16 v[120:123], v[136:139], v[176:179], v[120:123]
	v_mfma_f32_16x16x32_bf16 v[96:99], v[144:147], v[176:179], v[96:99]
	v_mfma_f32_16x16x32_bf16 v[104:107], v[136:139], v[184:187], v[104:107]
	v_mfma_f32_16x16x32_bf16 v[88:91], v[144:147], v[184:187], v[88:91]
	v_mfma_f32_16x16x32_bf16 v[84:87], v[136:139], v[250:253], v[84:87]
	v_mfma_f32_16x16x32_bf16 v[72:75], v[144:147], v[250:253], v[72:75]
	s_setprio 0
	s_setprio 1
	v_mfma_f32_16x16x32_bf16 v[124:127], v[148:151], v[164:167], v[124:127]
	v_mfma_f32_16x16x32_bf16 v[108:111], v[156:159], v[164:167], v[108:111]
	v_mfma_f32_16x16x32_bf16 v[116:119], v[148:151], v[172:175], v[116:119]
	v_mfma_f32_16x16x32_bf16 v[92:95], v[156:159], v[172:175], v[92:95]
	v_mfma_f32_16x16x32_bf16 v[100:103], v[148:151], v[180:183], v[100:103]
	v_mfma_f32_16x16x32_bf16 v[80:83], v[156:159], v[180:183], v[80:83]
	v_mfma_f32_16x16x32_bf16 v[76:79], v[148:151], v[188:191], v[76:79]
	v_mfma_f32_16x16x32_bf16 v[68:71], v[156:159], v[188:191], v[68:71]
	v_mfma_f32_16x16x32_bf16 v[124:127], v[152:155], v[168:171], v[124:127]
	v_mfma_f32_16x16x32_bf16 v[108:111], v[160:163], v[168:171], v[108:111]
	v_mfma_f32_16x16x32_bf16 v[116:119], v[152:155], v[176:179], v[116:119]
	v_mfma_f32_16x16x32_bf16 v[92:95], v[160:163], v[176:179], v[92:95]
	v_mfma_f32_16x16x32_bf16 v[100:103], v[152:155], v[184:187], v[100:103]
	v_mfma_f32_16x16x32_bf16 v[80:83], v[160:163], v[184:187], v[80:83]
	v_mfma_f32_16x16x32_bf16 v[76:79], v[152:155], v[250:253], v[76:79]
	v_mfma_f32_16x16x32_bf16 v[68:71], v[160:163], v[250:253], v[68:71]
	s_setprio 0
	s_barrier
	s_add_i32 s34, s89, s0
	s_mov_b32 m0, s34
	ds_read_b128 v[164:167], v0 offset:16384
	ds_read_b128 v[168:171], v0 offset:17408
	ds_read_b128 v[172:175], v0 offset:18432
	ds_read_b128 v[176:179], v0 offset:19456
	ds_read_b128 v[180:183], v0 offset:20480
	ds_read_b128 v[184:187], v0 offset:21504
	ds_read_b128 v[188:191], v0 offset:22528
	ds_read_b128 v[250:253], v0 offset:23552
	global_load_lds_dwordx4 v196, s[66:67]
	s_add_i32 m0, s34, 0x2000
	s_add_u32 s34, s66, 0x4000
	s_addc_u32 s35, s67, 0
	s_add_i32 s89, vcc_hi, s0
	global_load_lds_dwordx4 v200, s[66:67]
	s_mov_b32 m0, s89
	s_nop 0
	global_load_lds_dwordx4 v196, s[34:35]
	s_add_i32 m0, s89, 0x2000
	s_nop 0
	global_load_lds_dwordx4 v200, s[34:35]
	s_mov_b32 m0, s29
	s_nop 0
	global_load_lds_dwordx4 v198, s[94:95]
	s_mov_b32 m0, s45
	s_nop 0
	global_load_lds_dwordx4 v202, s[94:95]
	s_waitcnt vmcnt(8)
	s_waitcnt lgkmcnt(0)
	s_barrier
	s_setprio 1
	s_waitcnt lgkmcnt(0)
	v_mfma_f32_16x16x32_bf16 v[64:67], v[132:135], v[164:167], v[64:67]
	v_mfma_f32_16x16x32_bf16 v[56:59], v[140:143], v[164:167], v[56:59]
	v_mfma_f32_16x16x32_bf16 v[48:51], v[132:135], v[172:175], v[48:51]
	v_mfma_f32_16x16x32_bf16 v[40:43], v[140:143], v[172:175], v[40:43]
	v_mfma_f32_16x16x32_bf16 v[30:33], v[132:135], v[180:183], v[30:33]
	v_mfma_f32_16x16x32_bf16 v[26:29], v[140:143], v[180:183], v[26:29]
	v_mfma_f32_16x16x32_bf16 v[14:17], v[132:135], v[188:191], v[14:17]
	v_mfma_f32_16x16x32_bf16 v[10:13], v[140:143], v[188:191], v[10:13]
	v_mfma_f32_16x16x32_bf16 v[64:67], v[136:139], v[168:171], v[64:67]
	v_mfma_f32_16x16x32_bf16 v[56:59], v[144:147], v[168:171], v[56:59]
	v_mfma_f32_16x16x32_bf16 v[48:51], v[136:139], v[176:179], v[48:51]
	v_mfma_f32_16x16x32_bf16 v[40:43], v[144:147], v[176:179], v[40:43]
	v_mfma_f32_16x16x32_bf16 v[30:33], v[136:139], v[184:187], v[30:33]
	v_mfma_f32_16x16x32_bf16 v[26:29], v[144:147], v[184:187], v[26:29]
	v_mfma_f32_16x16x32_bf16 v[14:17], v[136:139], v[250:253], v[14:17]
	v_mfma_f32_16x16x32_bf16 v[10:13], v[144:147], v[250:253], v[10:13]
	s_setprio 0
	s_setprio 1
	v_mfma_f32_16x16x32_bf16 v[60:63], v[148:151], v[164:167], v[60:63]
	v_mfma_f32_16x16x32_bf16 v[52:55], v[156:159], v[164:167], v[52:55]
	v_mfma_f32_16x16x32_bf16 v[44:47], v[148:151], v[172:175], v[44:47]
	v_mfma_f32_16x16x32_bf16 v[36:39], v[156:159], v[172:175], v[36:39]
	v_mfma_f32_16x16x32_bf16 v[22:25], v[148:151], v[180:183], v[22:25]
	v_mfma_f32_16x16x32_bf16 v[18:21], v[156:159], v[180:183], v[18:21]
	v_mfma_f32_16x16x32_bf16 v[6:9], v[148:151], v[188:191], v[6:9]
	v_mfma_f32_16x16x32_bf16 v[2:5], v[156:159], v[188:191], v[2:5]
	v_mfma_f32_16x16x32_bf16 v[60:63], v[152:155], v[168:171], v[60:63]
	v_mfma_f32_16x16x32_bf16 v[52:55], v[160:163], v[168:171], v[52:55]
	v_mfma_f32_16x16x32_bf16 v[44:47], v[152:155], v[176:179], v[44:47]
	v_mfma_f32_16x16x32_bf16 v[36:39], v[160:163], v[176:179], v[36:39]
	v_mfma_f32_16x16x32_bf16 v[22:25], v[152:155], v[184:187], v[22:25]
	v_mfma_f32_16x16x32_bf16 v[18:21], v[160:163], v[184:187], v[18:21]
	v_mfma_f32_16x16x32_bf16 v[6:9], v[152:155], v[250:253], v[6:9]
	v_mfma_f32_16x16x32_bf16 v[2:5], v[160:163], v[250:253], v[2:5]
	s_setprio 0
	s_barrier
	s_add_i32 s89, 0, 0x18000
	s_add_i32 vcc_hi, 0, 0x1c000
	v_add_u32_e32 v144, s89, v217
	v_add_u32_e32 v160, vcc_hi, v217
	ds_read_b128 v[132:135], v144
	ds_read_b128 v[136:139], v144 offset:1024
	ds_read_b128 v[140:143], v144 offset:2048
	ds_read_b128 v[144:147], v144 offset:3072
	ds_read_b128 v[148:151], v160
	ds_read_b128 v[152:155], v160 offset:1024
	ds_read_b128 v[156:159], v160 offset:2048
	ds_read_b128 v[160:163], v160 offset:3072
	s_add_u32 s34, s94, 0x100000
	s_addc_u32 s35, s95, 0
	s_mov_b32 m0, s82
	ds_read_b128 v[164:167], v0 offset:32768
	ds_read_b128 v[168:171], v0 offset:33792
	ds_read_b128 v[172:175], v0 offset:34816
	ds_read_b128 v[176:179], v0 offset:35840
	ds_read_b128 v[180:183], v0 offset:36864
	ds_read_b128 v[184:187], v0 offset:37888
	ds_read_b128 v[188:191], v0 offset:38912
	ds_read_b128 v[250:253], v0 offset:39936
	global_load_lds_dwordx4 v198, s[34:35]
	s_mov_b32 m0, s90
	s_nop 0
	global_load_lds_dwordx4 v202, s[34:35]
	s_waitcnt vmcnt(8)
	s_waitcnt lgkmcnt(0)
	s_barrier
	s_setprio 1
	s_waitcnt lgkmcnt(0)
	v_mfma_f32_16x16x32_bf16 v[128:131], v[132:135], v[164:167], v[128:131]
	v_mfma_f32_16x16x32_bf16 v[112:115], v[140:143], v[164:167], v[112:115]
	v_mfma_f32_16x16x32_bf16 v[120:123], v[132:135], v[172:175], v[120:123]
	v_mfma_f32_16x16x32_bf16 v[96:99], v[140:143], v[172:175], v[96:99]
	v_mfma_f32_16x16x32_bf16 v[104:107], v[132:135], v[180:183], v[104:107]
	v_mfma_f32_16x16x32_bf16 v[88:91], v[140:143], v[180:183], v[88:91]
	v_mfma_f32_16x16x32_bf16 v[84:87], v[132:135], v[188:191], v[84:87]
	v_mfma_f32_16x16x32_bf16 v[72:75], v[140:143], v[188:191], v[72:75]
	v_mfma_f32_16x16x32_bf16 v[128:131], v[136:139], v[168:171], v[128:131]
	v_mfma_f32_16x16x32_bf16 v[112:115], v[144:147], v[168:171], v[112:115]
	v_mfma_f32_16x16x32_bf16 v[120:123], v[136:139], v[176:179], v[120:123]
	v_mfma_f32_16x16x32_bf16 v[96:99], v[144:147], v[176:179], v[96:99]
	v_mfma_f32_16x16x32_bf16 v[104:107], v[136:139], v[184:187], v[104:107]
	v_mfma_f32_16x16x32_bf16 v[88:91], v[144:147], v[184:187], v[88:91]
	v_mfma_f32_16x16x32_bf16 v[84:87], v[136:139], v[250:253], v[84:87]
	v_mfma_f32_16x16x32_bf16 v[72:75], v[144:147], v[250:253], v[72:75]
	s_setprio 0
	s_setprio 1
	v_mfma_f32_16x16x32_bf16 v[124:127], v[148:151], v[164:167], v[124:127]
	v_mfma_f32_16x16x32_bf16 v[108:111], v[156:159], v[164:167], v[108:111]
	v_mfma_f32_16x16x32_bf16 v[116:119], v[148:151], v[172:175], v[116:119]
	v_mfma_f32_16x16x32_bf16 v[92:95], v[156:159], v[172:175], v[92:95]
	v_mfma_f32_16x16x32_bf16 v[100:103], v[148:151], v[180:183], v[100:103]
	v_mfma_f32_16x16x32_bf16 v[80:83], v[156:159], v[180:183], v[80:83]
	v_mfma_f32_16x16x32_bf16 v[76:79], v[148:151], v[188:191], v[76:79]
	v_mfma_f32_16x16x32_bf16 v[68:71], v[156:159], v[188:191], v[68:71]
	v_mfma_f32_16x16x32_bf16 v[124:127], v[152:155], v[168:171], v[124:127]
	v_mfma_f32_16x16x32_bf16 v[108:111], v[160:163], v[168:171], v[108:111]
	v_mfma_f32_16x16x32_bf16 v[116:119], v[152:155], v[176:179], v[116:119]
	v_mfma_f32_16x16x32_bf16 v[92:95], v[160:163], v[176:179], v[92:95]
	v_mfma_f32_16x16x32_bf16 v[100:103], v[152:155], v[184:187], v[100:103]
	v_mfma_f32_16x16x32_bf16 v[80:83], v[160:163], v[184:187], v[80:83]
	v_mfma_f32_16x16x32_bf16 v[76:79], v[152:155], v[250:253], v[76:79]
	v_mfma_f32_16x16x32_bf16 v[68:71], v[160:163], v[250:253], v[68:71]
	s_setprio 0
	s_barrier
	s_add_u32 s34, s66, 0x8000
	s_addc_u32 s35, s67, 0
	s_add_i32 s89, s89, s0
	s_mov_b32 m0, s89
	ds_read_b128 v[164:167], v0 offset:49152
	ds_read_b128 v[168:171], v0 offset:50176
	ds_read_b128 v[172:175], v0 offset:51200
	ds_read_b128 v[176:179], v0 offset:52224
	ds_read_b128 v[180:183], v0 offset:53248
	ds_read_b128 v[184:187], v0 offset:54272
	ds_read_b128 v[188:191], v0 offset:55296
	ds_read_b128 v[250:253], v0 offset:56320
	global_load_lds_dwordx4 v196, s[34:35]
	s_add_i32 m0, s89, 0x2000
	v_lshl_add_u64 v[210:211], s[34:35], 0, v[200:201]
	s_add_u32 s34, s66, 0xc000
	s_addc_u32 s35, s67, 0
	s_add_i32 s66, vcc_hi, s0
	global_load_lds_dwordx4 v[210:211], off
	s_mov_b32 m0, s66
	s_nop 0
	global_load_lds_dwordx4 v196, s[34:35]
	s_add_i32 m0, s66, 0x2000
	s_nop 0
	global_load_lds_dwordx4 v200, s[34:35]
	s_mov_b32 m0, s91
	s_nop 0
	s_add_u32 s100, s94, s92
	s_addc_u32 s101, s95, s93
	global_load_lds_dwordx4 v198, s[100:101]
	s_mov_b32 m0, s30
	s_nop 0
	s_add_u32 s100, s94, s92
	s_addc_u32 s101, s95, s93
	global_load_lds_dwordx4 v202, s[100:101]
	s_waitcnt vmcnt(8)
	s_waitcnt lgkmcnt(0)
	s_barrier
	s_setprio 1
	s_waitcnt lgkmcnt(0)
	v_mfma_f32_16x16x32_bf16 v[64:67], v[132:135], v[164:167], v[64:67]
	v_mfma_f32_16x16x32_bf16 v[56:59], v[140:143], v[164:167], v[56:59]
	v_mfma_f32_16x16x32_bf16 v[48:51], v[132:135], v[172:175], v[48:51]
	v_mfma_f32_16x16x32_bf16 v[40:43], v[140:143], v[172:175], v[40:43]
	v_mfma_f32_16x16x32_bf16 v[30:33], v[132:135], v[180:183], v[30:33]
	v_mfma_f32_16x16x32_bf16 v[26:29], v[140:143], v[180:183], v[26:29]
	v_mfma_f32_16x16x32_bf16 v[14:17], v[132:135], v[188:191], v[14:17]
	v_mfma_f32_16x16x32_bf16 v[10:13], v[140:143], v[188:191], v[10:13]
	v_mfma_f32_16x16x32_bf16 v[64:67], v[136:139], v[168:171], v[64:67]
	v_mfma_f32_16x16x32_bf16 v[56:59], v[144:147], v[168:171], v[56:59]
	v_mfma_f32_16x16x32_bf16 v[48:51], v[136:139], v[176:179], v[48:51]
	v_mfma_f32_16x16x32_bf16 v[40:43], v[144:147], v[176:179], v[40:43]
	v_mfma_f32_16x16x32_bf16 v[30:33], v[136:139], v[184:187], v[30:33]
	v_mfma_f32_16x16x32_bf16 v[26:29], v[144:147], v[184:187], v[26:29]
	v_mfma_f32_16x16x32_bf16 v[14:17], v[136:139], v[250:253], v[14:17]
	v_mfma_f32_16x16x32_bf16 v[10:13], v[144:147], v[250:253], v[10:13]
	s_setprio 0
	s_setprio 1
	v_mfma_f32_16x16x32_bf16 v[60:63], v[148:151], v[164:167], v[60:63]
	v_mfma_f32_16x16x32_bf16 v[52:55], v[156:159], v[164:167], v[52:55]
	v_mfma_f32_16x16x32_bf16 v[44:47], v[148:151], v[172:175], v[44:47]
	v_mfma_f32_16x16x32_bf16 v[36:39], v[156:159], v[172:175], v[36:39]
	v_mfma_f32_16x16x32_bf16 v[22:25], v[148:151], v[180:183], v[22:25]
	v_mfma_f32_16x16x32_bf16 v[18:21], v[156:159], v[180:183], v[18:21]
	v_mfma_f32_16x16x32_bf16 v[6:9], v[148:151], v[188:191], v[6:9]
	v_mfma_f32_16x16x32_bf16 v[2:5], v[156:159], v[188:191], v[2:5]
	v_mfma_f32_16x16x32_bf16 v[60:63], v[152:155], v[168:171], v[60:63]
	v_mfma_f32_16x16x32_bf16 v[52:55], v[160:163], v[168:171], v[52:55]
	v_mfma_f32_16x16x32_bf16 v[44:47], v[152:155], v[176:179], v[44:47]
	v_mfma_f32_16x16x32_bf16 v[36:39], v[160:163], v[176:179], v[36:39]
	v_mfma_f32_16x16x32_bf16 v[22:25], v[152:155], v[184:187], v[22:25]
	v_mfma_f32_16x16x32_bf16 v[18:21], v[160:163], v[184:187], v[18:21]
	v_mfma_f32_16x16x32_bf16 v[6:9], v[152:155], v[250:253], v[6:9]
	v_mfma_f32_16x16x32_bf16 v[2:5], v[160:163], v[250:253], v[2:5]
	s_setprio 0
	s_barrier
	s_add_u32 s70, s70, 0x10000
	s_addc_u32 s80, s80, 0
	s_add_u32 s8, s8, 0x100
	s_addc_u32 s9, s9, 0
	s_cmp_lt_i32 vcc_lo, s58
	s_mov_b32 s66, vcc_lo
	s_cbranch_scc1 .LBB0_324
	v_mov_b32_e32 v252, v212
	s_branch .LBB0_235

.LBB0_327:
	s_add_i32 s70, s8, 2
	s_add_u32 s9, s6, 0xfff00080
	s_addc_u32 s10, s7, -1
	s_add_i32 s34, 0, 0x10000
	s_cmp_eq_u32 s59, s8
	s_cselect_b32 s11, s65, s10
	s_cselect_b32 s10, s64, s9
	v_add_u32_e32 v0, s34, v217
	s_cselect_b32 s9, s53, s67
	s_cselect_b32 s8, s52, s66
	s_add_i32 s35, 0, 0x14000
	ds_read_b128 v[132:135], v0
	ds_read_b128 v[136:139], v0 offset:1024
	ds_read_b128 v[140:143], v0 offset:2048
	ds_read_b128 v[144:147], v0 offset:3072
	v_add_u32_e32 v0, s35, v217
	ds_read_b128 v[148:151], v0
	ds_read_b128 v[152:155], v0 offset:1024
	ds_read_b128 v[156:159], v0 offset:2048
	ds_read_b128 v[160:163], v0 offset:3072
	v_add_u32_e32 v0, 0, v216
	s_add_i32 m0, s29, 0xc000
	ds_read_b128 v[164:167], v0
	ds_read_b128 v[168:171], v0 offset:1024
	ds_read_b128 v[172:175], v0 offset:2048
	ds_read_b128 v[176:179], v0 offset:3072
	ds_read_b128 v[180:183], v0 offset:4096
	ds_read_b128 v[184:187], v0 offset:5120
	ds_read_b128 v[188:191], v0 offset:6144
	ds_read_b128 v[250:253], v0 offset:7168
	global_load_lds_dwordx4 v204, s[6:7]
	s_add_i32 m0, s29, 0xe000
	s_nop 0
	global_load_lds_dwordx4 v206, s[6:7]
	s_waitcnt vmcnt(8)
	s_waitcnt lgkmcnt(0)
	s_barrier
	s_setprio 1
	s_waitcnt lgkmcnt(0)
	v_mfma_i32_16x16x64_i8 v[128:131], v[132:135], v[164:167], v[128:131]
	v_mfma_i32_16x16x64_i8 v[112:115], v[140:143], v[164:167], v[112:115]
	v_mfma_i32_16x16x64_i8 v[120:123], v[132:135], v[172:175], v[120:123]
	v_mfma_i32_16x16x64_i8 v[96:99], v[140:143], v[172:175], v[96:99]
	v_mfma_i32_16x16x64_i8 v[104:107], v[132:135], v[180:183], v[104:107]
	v_mfma_i32_16x16x64_i8 v[88:91], v[140:143], v[180:183], v[88:91]
	v_mfma_i32_16x16x64_i8 v[84:87], v[132:135], v[188:191], v[84:87]
	v_mfma_i32_16x16x64_i8 v[72:75], v[140:143], v[188:191], v[72:75]
	v_mfma_i32_16x16x64_i8 v[128:131], v[136:139], v[168:171], v[128:131]
	v_mfma_i32_16x16x64_i8 v[112:115], v[144:147], v[168:171], v[112:115]
	v_mfma_i32_16x16x64_i8 v[120:123], v[136:139], v[176:179], v[120:123]
	v_mfma_i32_16x16x64_i8 v[96:99], v[144:147], v[176:179], v[96:99]
	v_mfma_i32_16x16x64_i8 v[104:107], v[136:139], v[184:187], v[104:107]
	v_mfma_i32_16x16x64_i8 v[88:91], v[144:147], v[184:187], v[88:91]
	v_mfma_i32_16x16x64_i8 v[84:87], v[136:139], v[250:253], v[84:87]
	v_mfma_i32_16x16x64_i8 v[72:75], v[144:147], v[250:253], v[72:75]
	s_setprio 0
	s_setprio 1
	v_mfma_i32_16x16x64_i8 v[124:127], v[148:151], v[164:167], v[124:127]
	v_mfma_i32_16x16x64_i8 v[108:111], v[156:159], v[164:167], v[108:111]
	v_mfma_i32_16x16x64_i8 v[116:119], v[148:151], v[172:175], v[116:119]
	v_mfma_i32_16x16x64_i8 v[92:95], v[156:159], v[172:175], v[92:95]
	v_mfma_i32_16x16x64_i8 v[100:103], v[148:151], v[180:183], v[100:103]
	v_mfma_i32_16x16x64_i8 v[80:83], v[156:159], v[180:183], v[80:83]
	v_mfma_i32_16x16x64_i8 v[76:79], v[148:151], v[188:191], v[76:79]
	v_mfma_i32_16x16x64_i8 v[68:71], v[156:159], v[188:191], v[68:71]
	v_mfma_i32_16x16x64_i8 v[124:127], v[152:155], v[168:171], v[124:127]
	v_mfma_i32_16x16x64_i8 v[108:111], v[160:163], v[168:171], v[108:111]
	v_mfma_i32_16x16x64_i8 v[116:119], v[152:155], v[176:179], v[116:119]
	v_mfma_i32_16x16x64_i8 v[92:95], v[160:163], v[176:179], v[92:95]
	v_mfma_i32_16x16x64_i8 v[100:103], v[152:155], v[184:187], v[100:103]
	v_mfma_i32_16x16x64_i8 v[80:83], v[160:163], v[184:187], v[80:83]
	v_mfma_i32_16x16x64_i8 v[76:79], v[152:155], v[250:253], v[76:79]
	v_mfma_i32_16x16x64_i8 v[68:71], v[160:163], v[250:253], v[68:71]
	s_setprio 0
	s_barrier
	s_add_i32 s34, s34, s0
	s_mov_b32 m0, s34
	ds_read_b128 v[164:167], v0 offset:16384
	ds_read_b128 v[168:171], v0 offset:17408
	ds_read_b128 v[172:175], v0 offset:18432
	ds_read_b128 v[176:179], v0 offset:19456
	ds_read_b128 v[180:183], v0 offset:20480
	ds_read_b128 v[184:187], v0 offset:21504
	ds_read_b128 v[188:191], v0 offset:22528
	ds_read_b128 v[250:253], v0 offset:23552
	global_load_lds_dwordx4 v196, s[8:9]
	s_add_i32 m0, s34, 0x2000
	s_add_u32 s94, s8, 0x4000
	s_addc_u32 s95, s9, 0
	s_add_i32 s34, s35, s0
	global_load_lds_dwordx4 v200, s[8:9]
	s_mov_b32 m0, s34
	v_lshl_add_u64 v[194:195], s[10:11], 0, v[202:203]
	global_load_lds_dwordx4 v196, s[94:95]
	s_add_i32 m0, s34, 0x2000
	s_nop 0
	global_load_lds_dwordx4 v200, s[94:95]
	v_lshl_add_u64 v[192:193], s[10:11], 0, v[198:199]
	s_mov_b32 m0, s29
	s_nop 0
	global_load_lds_dwordx4 v198, s[10:11]
	s_mov_b32 m0, s45
	s_nop 0
	global_load_lds_dwordx4 v202, s[10:11]
	s_waitcnt vmcnt(8)
	s_waitcnt lgkmcnt(0)
	s_barrier
	s_setprio 1
	s_waitcnt lgkmcnt(0)
	v_mfma_i32_16x16x64_i8 v[64:67], v[132:135], v[164:167], v[64:67]
	v_mfma_i32_16x16x64_i8 v[56:59], v[140:143], v[164:167], v[56:59]
	v_mfma_i32_16x16x64_i8 v[48:51], v[132:135], v[172:175], v[48:51]
	v_mfma_i32_16x16x64_i8 v[40:43], v[140:143], v[172:175], v[40:43]
	v_mfma_i32_16x16x64_i8 v[30:33], v[132:135], v[180:183], v[30:33]
	v_mfma_i32_16x16x64_i8 v[26:29], v[140:143], v[180:183], v[26:29]
	v_mfma_i32_16x16x64_i8 v[14:17], v[132:135], v[188:191], v[14:17]
	v_mfma_i32_16x16x64_i8 v[10:13], v[140:143], v[188:191], v[10:13]
	v_mfma_i32_16x16x64_i8 v[64:67], v[136:139], v[168:171], v[64:67]
	v_mfma_i32_16x16x64_i8 v[56:59], v[144:147], v[168:171], v[56:59]
	v_mfma_i32_16x16x64_i8 v[48:51], v[136:139], v[176:179], v[48:51]
	v_mfma_i32_16x16x64_i8 v[40:43], v[144:147], v[176:179], v[40:43]
	v_mfma_i32_16x16x64_i8 v[30:33], v[136:139], v[184:187], v[30:33]
	v_mfma_i32_16x16x64_i8 v[26:29], v[144:147], v[184:187], v[26:29]
	v_mfma_i32_16x16x64_i8 v[14:17], v[136:139], v[250:253], v[14:17]
	v_mfma_i32_16x16x64_i8 v[10:13], v[144:147], v[250:253], v[10:13]
	s_setprio 0
	s_setprio 1
	v_mfma_i32_16x16x64_i8 v[60:63], v[148:151], v[164:167], v[60:63]
	v_mfma_i32_16x16x64_i8 v[52:55], v[156:159], v[164:167], v[52:55]
	v_mfma_i32_16x16x64_i8 v[44:47], v[148:151], v[172:175], v[44:47]
	v_mfma_i32_16x16x64_i8 v[36:39], v[156:159], v[172:175], v[36:39]
	v_mfma_i32_16x16x64_i8 v[22:25], v[148:151], v[180:183], v[22:25]
	v_mfma_i32_16x16x64_i8 v[18:21], v[156:159], v[180:183], v[18:21]
	v_mfma_i32_16x16x64_i8 v[6:9], v[148:151], v[188:191], v[6:9]
	v_mfma_i32_16x16x64_i8 v[2:5], v[156:159], v[188:191], v[2:5]
	v_mfma_i32_16x16x64_i8 v[60:63], v[152:155], v[168:171], v[60:63]
	v_mfma_i32_16x16x64_i8 v[52:55], v[160:163], v[168:171], v[52:55]
	v_mfma_i32_16x16x64_i8 v[44:47], v[152:155], v[176:179], v[44:47]
	v_mfma_i32_16x16x64_i8 v[36:39], v[160:163], v[176:179], v[36:39]
	v_mfma_i32_16x16x64_i8 v[22:25], v[152:155], v[184:187], v[22:25]
	v_mfma_i32_16x16x64_i8 v[18:21], v[160:163], v[184:187], v[18:21]
	v_mfma_i32_16x16x64_i8 v[6:9], v[152:155], v[250:253], v[6:9]
	v_mfma_i32_16x16x64_i8 v[2:5], v[160:163], v[250:253], v[2:5]
	s_setprio 0
	s_barrier
	s_add_i32 s34, 0, 0x18000
	s_add_i32 s35, 0, 0x1c000
	v_add_u32_e32 v144, s34, v217
	v_add_u32_e32 v160, s35, v217
	ds_read_b128 v[132:135], v144
	ds_read_b128 v[136:139], v144 offset:1024
	ds_read_b128 v[140:143], v144 offset:2048
	ds_read_b128 v[144:147], v144 offset:3072
	ds_read_b128 v[148:151], v160
	ds_read_b128 v[152:155], v160 offset:1024
	ds_read_b128 v[156:159], v160 offset:2048
	ds_read_b128 v[160:163], v160 offset:3072
	s_add_u32 s10, s10, 0x100000
	s_addc_u32 s11, s11, 0
	s_mov_b32 m0, s82
	ds_read_b128 v[164:167], v0 offset:32768
	ds_read_b128 v[168:171], v0 offset:33792
	ds_read_b128 v[172:175], v0 offset:34816
	ds_read_b128 v[176:179], v0 offset:35840
	ds_read_b128 v[180:183], v0 offset:36864
	ds_read_b128 v[184:187], v0 offset:37888
	ds_read_b128 v[188:191], v0 offset:38912
	ds_read_b128 v[250:253], v0 offset:39936
	global_load_lds_dwordx4 v198, s[10:11]
	s_mov_b32 m0, s90
	s_nop 0
	global_load_lds_dwordx4 v202, s[10:11]
	s_waitcnt vmcnt(8)
	s_waitcnt lgkmcnt(0)
	s_barrier
	s_setprio 1
	s_waitcnt lgkmcnt(0)
	v_mfma_i32_16x16x64_i8 v[128:131], v[132:135], v[164:167], v[128:131]
	v_mfma_i32_16x16x64_i8 v[112:115], v[140:143], v[164:167], v[112:115]
	v_mfma_i32_16x16x64_i8 v[120:123], v[132:135], v[172:175], v[120:123]
	v_mfma_i32_16x16x64_i8 v[96:99], v[140:143], v[172:175], v[96:99]
	v_mfma_i32_16x16x64_i8 v[104:107], v[132:135], v[180:183], v[104:107]
	v_mfma_i32_16x16x64_i8 v[88:91], v[140:143], v[180:183], v[88:91]
	v_mfma_i32_16x16x64_i8 v[84:87], v[132:135], v[188:191], v[84:87]
	v_mfma_i32_16x16x64_i8 v[72:75], v[140:143], v[188:191], v[72:75]
	v_mfma_i32_16x16x64_i8 v[128:131], v[136:139], v[168:171], v[128:131]
	v_mfma_i32_16x16x64_i8 v[112:115], v[144:147], v[168:171], v[112:115]
	v_mfma_i32_16x16x64_i8 v[120:123], v[136:139], v[176:179], v[120:123]
	v_mfma_i32_16x16x64_i8 v[96:99], v[144:147], v[176:179], v[96:99]
	v_mfma_i32_16x16x64_i8 v[104:107], v[136:139], v[184:187], v[104:107]
	v_mfma_i32_16x16x64_i8 v[88:91], v[144:147], v[184:187], v[88:91]
	v_mfma_i32_16x16x64_i8 v[84:87], v[136:139], v[250:253], v[84:87]
	v_mfma_i32_16x16x64_i8 v[72:75], v[144:147], v[250:253], v[72:75]
	s_setprio 0
	s_setprio 1
	v_mfma_i32_16x16x64_i8 v[124:127], v[148:151], v[164:167], v[124:127]
	v_mfma_i32_16x16x64_i8 v[108:111], v[156:159], v[164:167], v[108:111]
	v_mfma_i32_16x16x64_i8 v[116:119], v[148:151], v[172:175], v[116:119]
	v_mfma_i32_16x16x64_i8 v[92:95], v[156:159], v[172:175], v[92:95]
	v_mfma_i32_16x16x64_i8 v[100:103], v[148:151], v[180:183], v[100:103]
	v_mfma_i32_16x16x64_i8 v[80:83], v[156:159], v[180:183], v[80:83]
	v_mfma_i32_16x16x64_i8 v[76:79], v[148:151], v[188:191], v[76:79]
	v_mfma_i32_16x16x64_i8 v[68:71], v[156:159], v[188:191], v[68:71]
	v_mfma_i32_16x16x64_i8 v[124:127], v[152:155], v[168:171], v[124:127]
	v_mfma_i32_16x16x64_i8 v[108:111], v[160:163], v[168:171], v[108:111]
	v_mfma_i32_16x16x64_i8 v[116:119], v[152:155], v[176:179], v[116:119]
	v_mfma_i32_16x16x64_i8 v[92:95], v[160:163], v[176:179], v[92:95]
	v_mfma_i32_16x16x64_i8 v[100:103], v[152:155], v[184:187], v[100:103]
	v_mfma_i32_16x16x64_i8 v[80:83], v[160:163], v[184:187], v[80:83]
	v_mfma_i32_16x16x64_i8 v[76:79], v[152:155], v[250:253], v[76:79]
	v_mfma_i32_16x16x64_i8 v[68:71], v[160:163], v[250:253], v[68:71]
	s_setprio 0
	s_barrier
	s_add_u32 s10, s8, 0x8000
	s_addc_u32 s11, s9, 0
	s_add_i32 s34, s34, s0
	s_mov_b32 m0, s34
	ds_read_b128 v[164:167], v0 offset:49152
	ds_read_b128 v[168:171], v0 offset:50176
	ds_read_b128 v[172:175], v0 offset:51200
	ds_read_b128 v[176:179], v0 offset:52224
	ds_read_b128 v[180:183], v0 offset:53248
	ds_read_b128 v[184:187], v0 offset:54272
	ds_read_b128 v[188:191], v0 offset:55296
	ds_read_b128 v[250:253], v0 offset:56320
	global_load_lds_dwordx4 v196, s[10:11]
	s_add_i32 m0, s34, 0x2000
	s_add_u32 s8, s8, 0xc000
	v_lshl_add_u64 v[210:211], s[10:11], 0, v[200:201]
	s_addc_u32 s9, s9, 0
	s_add_i32 s10, s35, s0
	global_load_lds_dwordx4 v[210:211], off
	s_mov_b32 m0, s10
	v_lshl_add_u64 v[192:193], v[192:193], 0, s[92:93]
	global_load_lds_dwordx4 v196, s[8:9]
	s_add_i32 m0, s10, 0x2000
	s_nop 0
	global_load_lds_dwordx4 v200, s[8:9]
	s_mov_b32 m0, s91
	s_nop 0
	global_load_lds_dwordx4 v[192:193], off
	v_lshl_add_u64 v[192:193], v[194:195], 0, s[92:93]
	s_mov_b32 m0, s30
	s_nop 0
	global_load_lds_dwordx4 v[192:193], off
	s_waitcnt vmcnt(8)
	s_waitcnt lgkmcnt(0)
	s_barrier
	s_setprio 1
	s_waitcnt lgkmcnt(0)
	v_mfma_i32_16x16x64_i8 v[64:67], v[132:135], v[164:167], v[64:67]
	v_mfma_i32_16x16x64_i8 v[56:59], v[140:143], v[164:167], v[56:59]
	v_mfma_i32_16x16x64_i8 v[48:51], v[132:135], v[172:175], v[48:51]
	v_mfma_i32_16x16x64_i8 v[40:43], v[140:143], v[172:175], v[40:43]
	v_mfma_i32_16x16x64_i8 v[30:33], v[132:135], v[180:183], v[30:33]
	v_mfma_i32_16x16x64_i8 v[26:29], v[140:143], v[180:183], v[26:29]
	v_mfma_i32_16x16x64_i8 v[14:17], v[132:135], v[188:191], v[14:17]
	v_mfma_i32_16x16x64_i8 v[10:13], v[140:143], v[188:191], v[10:13]
	v_mfma_i32_16x16x64_i8 v[64:67], v[136:139], v[168:171], v[64:67]
	v_mfma_i32_16x16x64_i8 v[56:59], v[144:147], v[168:171], v[56:59]
	v_mfma_i32_16x16x64_i8 v[48:51], v[136:139], v[176:179], v[48:51]
	v_mfma_i32_16x16x64_i8 v[40:43], v[144:147], v[176:179], v[40:43]
	v_mfma_i32_16x16x64_i8 v[30:33], v[136:139], v[184:187], v[30:33]
	v_mfma_i32_16x16x64_i8 v[26:29], v[144:147], v[184:187], v[26:29]
	v_mfma_i32_16x16x64_i8 v[14:17], v[136:139], v[250:253], v[14:17]
	v_mfma_i32_16x16x64_i8 v[10:13], v[144:147], v[250:253], v[10:13]
	s_setprio 0
	s_setprio 1
	v_mfma_i32_16x16x64_i8 v[60:63], v[148:151], v[164:167], v[60:63]
	v_mfma_i32_16x16x64_i8 v[52:55], v[156:159], v[164:167], v[52:55]
	v_mfma_i32_16x16x64_i8 v[44:47], v[148:151], v[172:175], v[44:47]
	v_mfma_i32_16x16x64_i8 v[36:39], v[156:159], v[172:175], v[36:39]
	v_mfma_i32_16x16x64_i8 v[22:25], v[148:151], v[180:183], v[22:25]
	v_mfma_i32_16x16x64_i8 v[18:21], v[156:159], v[180:183], v[18:21]
	v_mfma_i32_16x16x64_i8 v[6:9], v[148:151], v[188:191], v[6:9]
	v_mfma_i32_16x16x64_i8 v[2:5], v[156:159], v[188:191], v[2:5]
	v_mfma_i32_16x16x64_i8 v[60:63], v[152:155], v[168:171], v[60:63]
	v_mfma_i32_16x16x64_i8 v[52:55], v[160:163], v[168:171], v[52:55]
	v_mfma_i32_16x16x64_i8 v[44:47], v[152:155], v[176:179], v[44:47]
	v_mfma_i32_16x16x64_i8 v[36:39], v[160:163], v[176:179], v[36:39]
	v_mfma_i32_16x16x64_i8 v[22:25], v[152:155], v[184:187], v[22:25]
	v_mfma_i32_16x16x64_i8 v[18:21], v[160:163], v[184:187], v[18:21]
	v_mfma_i32_16x16x64_i8 v[6:9], v[152:155], v[250:253], v[6:9]
	v_mfma_i32_16x16x64_i8 v[2:5], v[160:163], v[250:253], v[2:5]
	s_setprio 0
	s_barrier
	s_add_u32 s66, s66, 0x10000
	s_addc_u32 s67, s67, 0
	s_add_u32 s6, s6, 0x100
	s_addc_u32 s7, s7, 0
	s_cmp_ge_i32 s70, s58
	s_mov_b32 s8, s70
	s_cbranch_scc0 .LBB0_327
	v_mov_b32_e32 v252, v212
	v_cndmask_b32_e64 v0, 0, 1, s[46:47]
	v_cmp_ne_u32_e64 s[6:7], 1, v0
	s_andn2_b64 vcc, exec, s[46:47]
	s_cbranch_vccz .LBB0_236
	s_branch .LBB0_237

.LBB0_707:
	s_add_u32 s34, s50, 0xfff80080
	s_addc_u32 s35, s51, -1
	s_add_i32 s61, 0, 0x10000
	s_cmp_eq_u32 s60, 4
	s_cselect_b32 s55, s23, s35
	s_cselect_b32 s54, s22, s34
	v_add_u32_e32 v0, s61, v202
	s_cselect_b32 s53, s43, s59
	s_cselect_b32 s52, s42, s21
	s_add_i32 s62, 0, 0x14000
	ds_read_b128 v[164:167], v0
	ds_read_b128 v[168:171], v0 offset:1024
	ds_read_b128 v[172:175], v0 offset:2048
	ds_read_b128 v[176:179], v0 offset:3072
	v_add_u32_e32 v0, s62, v202
	ds_read_b128 v[192:195], v0
	ds_read_b128 v[196:199], v0 offset:1024
	ds_read_b128 v[204:207], v0 offset:2048
	ds_read_b128 v[210:213], v0 offset:3072
	s_add_i32 m0, s29, 0xc000
	ds_read_b128 v[216:219], v203
	ds_read_b128 v[220:223], v203 offset:1024
	ds_read_b128 v[224:227], v203 offset:2048
	ds_read_b128 v[228:231], v203 offset:3072
	ds_read_b128 v[232:235], v203 offset:4096
	ds_read_b128 v[236:239], v203 offset:5120
	ds_read_b128 v[240:243], v203 offset:6144
	ds_read_b128 v[244:247], v203 offset:7168
	global_load_lds_dwordx4 v188, s[50:51]
	s_add_i32 m0, s29, 0xe000
	s_nop 0
	global_load_lds_dwordx4 v190, s[50:51]
	s_waitcnt vmcnt(8)
	s_waitcnt lgkmcnt(0)
	s_barrier
	s_setprio 1
	s_waitcnt lgkmcnt(0)
	v_mfma_f32_16x16x32_bf16 v[160:163], v[164:167], v[216:219], v[160:163]
	v_mfma_f32_16x16x32_bf16 v[156:159], v[172:175], v[216:219], v[156:159]
	v_mfma_f32_16x16x32_bf16 v[144:147], v[164:167], v[224:227], v[144:147]
	v_mfma_f32_16x16x32_bf16 v[140:143], v[172:175], v[224:227], v[140:143]
	v_mfma_f32_16x16x32_bf16 v[128:131], v[164:167], v[232:235], v[128:131]
	v_mfma_f32_16x16x32_bf16 v[124:127], v[172:175], v[232:235], v[124:127]
	v_mfma_f32_16x16x32_bf16 v[112:115], v[164:167], v[240:243], v[112:115]
	v_mfma_f32_16x16x32_bf16 v[108:111], v[172:175], v[240:243], v[108:111]
	v_mfma_f32_16x16x32_bf16 v[160:163], v[168:171], v[220:223], v[160:163]
	v_mfma_f32_16x16x32_bf16 v[156:159], v[176:179], v[220:223], v[156:159]
	v_mfma_f32_16x16x32_bf16 v[144:147], v[168:171], v[228:231], v[144:147]
	v_mfma_f32_16x16x32_bf16 v[140:143], v[176:179], v[228:231], v[140:143]
	v_mfma_f32_16x16x32_bf16 v[128:131], v[168:171], v[236:239], v[128:131]
	v_mfma_f32_16x16x32_bf16 v[124:127], v[176:179], v[236:239], v[124:127]
	v_mfma_f32_16x16x32_bf16 v[112:115], v[168:171], v[244:247], v[112:115]
	v_mfma_f32_16x16x32_bf16 v[108:111], v[176:179], v[244:247], v[108:111]
	s_setprio 0
	s_setprio 1
	v_mfma_f32_16x16x32_bf16 v[152:155], v[192:195], v[216:219], v[152:155]
	v_mfma_f32_16x16x32_bf16 v[148:151], v[204:207], v[216:219], v[148:151]
	v_mfma_f32_16x16x32_bf16 v[136:139], v[192:195], v[224:227], v[136:139]
	v_mfma_f32_16x16x32_bf16 v[132:135], v[204:207], v[224:227], v[132:135]
	v_mfma_f32_16x16x32_bf16 v[120:123], v[192:195], v[232:235], v[120:123]
	v_mfma_f32_16x16x32_bf16 v[116:119], v[204:207], v[232:235], v[116:119]
	v_mfma_f32_16x16x32_bf16 v[104:107], v[192:195], v[240:243], v[104:107]
	v_mfma_f32_16x16x32_bf16 v[100:103], v[204:207], v[240:243], v[100:103]
	v_mfma_f32_16x16x32_bf16 v[152:155], v[196:199], v[220:223], v[152:155]
	v_mfma_f32_16x16x32_bf16 v[148:151], v[210:213], v[220:223], v[148:151]
	v_mfma_f32_16x16x32_bf16 v[136:139], v[196:199], v[228:231], v[136:139]
	v_mfma_f32_16x16x32_bf16 v[132:135], v[210:213], v[228:231], v[132:135]
	v_mfma_f32_16x16x32_bf16 v[120:123], v[196:199], v[236:239], v[120:123]
	v_mfma_f32_16x16x32_bf16 v[116:119], v[210:213], v[236:239], v[116:119]
	v_mfma_f32_16x16x32_bf16 v[104:107], v[196:199], v[244:247], v[104:107]
	v_mfma_f32_16x16x32_bf16 v[100:103], v[210:213], v[244:247], v[100:103]
	s_setprio 0
	s_barrier
	s_add_i32 s34, s61, s0
	s_mov_b32 m0, s34
	ds_read_b128 v[216:219], v203 offset:16384
	ds_read_b128 v[220:223], v203 offset:17408
	ds_read_b128 v[224:227], v203 offset:18432
	ds_read_b128 v[228:231], v203 offset:19456
	ds_read_b128 v[232:235], v203 offset:20480
	ds_read_b128 v[236:239], v203 offset:21504
	ds_read_b128 v[240:243], v203 offset:22528
	ds_read_b128 v[244:247], v203 offset:23552
	global_load_lds_dwordx4 v180, s[52:53]
	s_add_i32 m0, s34, 0x2000
	s_add_u32 s34, s52, 0x4000
	s_addc_u32 s35, s53, 0
	s_add_i32 s61, s62, s0
	global_load_lds_dwordx4 v184, s[52:53]
	s_mov_b32 m0, s61
	v_lshl_add_u64 v[248:249], s[54:55], 0, v[186:187]
	global_load_lds_dwordx4 v180, s[34:35]
	s_add_i32 m0, s61, 0x2000
	s_nop 0
	global_load_lds_dwordx4 v184, s[34:35]
	v_lshl_add_u64 v[200:201], s[54:55], 0, v[182:183]
	s_mov_b32 m0, s29
	s_nop 0
	global_load_lds_dwordx4 v182, s[54:55]
	s_mov_b32 m0, s45
	s_nop 0
	global_load_lds_dwordx4 v186, s[54:55]
	s_waitcnt vmcnt(8)
	s_waitcnt lgkmcnt(0)
	s_barrier
	s_setprio 1
	s_waitcnt lgkmcnt(0)
	v_mfma_f32_16x16x32_bf16 v[96:99], v[164:167], v[216:219], v[96:99]
	v_mfma_f32_16x16x32_bf16 v[92:95], v[172:175], v[216:219], v[92:95]
	v_mfma_f32_16x16x32_bf16 v[84:87], v[164:167], v[224:227], v[84:87]
	v_mfma_f32_16x16x32_bf16 v[76:79], v[172:175], v[224:227], v[76:79]
	v_mfma_f32_16x16x32_bf16 v[68:71], v[164:167], v[232:235], v[68:71]
	v_mfma_f32_16x16x32_bf16 v[60:63], v[172:175], v[232:235], v[60:63]
	v_mfma_f32_16x16x32_bf16 v[52:55], v[164:167], v[240:243], v[52:55]
	v_mfma_f32_16x16x32_bf16 v[44:47], v[172:175], v[240:243], v[44:47]
	v_mfma_f32_16x16x32_bf16 v[96:99], v[168:171], v[220:223], v[96:99]
	v_mfma_f32_16x16x32_bf16 v[92:95], v[176:179], v[220:223], v[92:95]
	v_mfma_f32_16x16x32_bf16 v[84:87], v[168:171], v[228:231], v[84:87]
	v_mfma_f32_16x16x32_bf16 v[76:79], v[176:179], v[228:231], v[76:79]
	v_mfma_f32_16x16x32_bf16 v[68:71], v[168:171], v[236:239], v[68:71]
	v_mfma_f32_16x16x32_bf16 v[60:63], v[176:179], v[236:239], v[60:63]
	v_mfma_f32_16x16x32_bf16 v[52:55], v[168:171], v[244:247], v[52:55]
	v_mfma_f32_16x16x32_bf16 v[44:47], v[176:179], v[244:247], v[44:47]
	s_setprio 0
	s_setprio 1
	v_mfma_f32_16x16x32_bf16 v[88:91], v[192:195], v[216:219], v[88:91]
	v_mfma_f32_16x16x32_bf16 v[80:83], v[204:207], v[216:219], v[80:83]
	v_mfma_f32_16x16x32_bf16 v[72:75], v[192:195], v[224:227], v[72:75]
	v_mfma_f32_16x16x32_bf16 v[64:67], v[204:207], v[224:227], v[64:67]
	v_mfma_f32_16x16x32_bf16 v[56:59], v[192:195], v[232:235], v[56:59]
	v_mfma_f32_16x16x32_bf16 v[48:51], v[204:207], v[232:235], v[48:51]
	v_mfma_f32_16x16x32_bf16 v[40:43], v[192:195], v[240:243], v[40:43]
	v_mfma_f32_16x16x32_bf16 v[36:39], v[204:207], v[240:243], v[36:39]
	v_mfma_f32_16x16x32_bf16 v[88:91], v[196:199], v[220:223], v[88:91]
	v_mfma_f32_16x16x32_bf16 v[80:83], v[210:213], v[220:223], v[80:83]
	v_mfma_f32_16x16x32_bf16 v[72:75], v[196:199], v[228:231], v[72:75]
	v_mfma_f32_16x16x32_bf16 v[64:67], v[210:213], v[228:231], v[64:67]
	v_mfma_f32_16x16x32_bf16 v[56:59], v[196:199], v[236:239], v[56:59]
	v_mfma_f32_16x16x32_bf16 v[48:51], v[210:213], v[236:239], v[48:51]
	v_mfma_f32_16x16x32_bf16 v[40:43], v[196:199], v[244:247], v[40:43]
	v_mfma_f32_16x16x32_bf16 v[36:39], v[210:213], v[244:247], v[36:39]
	s_setprio 0
	s_barrier
	s_add_i32 s61, 0, 0x18000
	v_add_u32_e32 v0, s61, v202
	s_add_i32 s62, 0, 0x1c000
	ds_read_b128 v[164:167], v0
	ds_read_b128 v[168:171], v0 offset:1024
	ds_read_b128 v[172:175], v0 offset:2048
	ds_read_b128 v[176:179], v0 offset:3072
	v_add_u32_e32 v0, s62, v202
	ds_read_b128 v[192:195], v0
	ds_read_b128 v[196:199], v0 offset:1024
	ds_read_b128 v[204:207], v0 offset:2048
	ds_read_b128 v[210:213], v0 offset:3072
	s_add_u32 s34, s54, 0x80000
	s_addc_u32 s35, s55, 0
	s_mov_b32 m0, s82
	ds_read_b128 v[216:219], v203 offset:32768
	ds_read_b128 v[220:223], v203 offset:33792
	ds_read_b128 v[224:227], v203 offset:34816
	ds_read_b128 v[228:231], v203 offset:35840
	ds_read_b128 v[232:235], v203 offset:36864
	ds_read_b128 v[236:239], v203 offset:37888
	ds_read_b128 v[240:243], v203 offset:38912
	ds_read_b128 v[244:247], v203 offset:39936
	global_load_lds_dwordx4 v182, s[34:35]
	s_mov_b32 m0, s90
	s_nop 0
	global_load_lds_dwordx4 v186, s[34:35]
	s_waitcnt vmcnt(8)
	s_waitcnt lgkmcnt(0)
	s_barrier
	s_setprio 1
	s_waitcnt lgkmcnt(0)
	v_mfma_f32_16x16x32_bf16 v[160:163], v[164:167], v[216:219], v[160:163]
	v_mfma_f32_16x16x32_bf16 v[156:159], v[172:175], v[216:219], v[156:159]
	v_mfma_f32_16x16x32_bf16 v[144:147], v[164:167], v[224:227], v[144:147]
	v_mfma_f32_16x16x32_bf16 v[140:143], v[172:175], v[224:227], v[140:143]
	v_mfma_f32_16x16x32_bf16 v[128:131], v[164:167], v[232:235], v[128:131]
	v_mfma_f32_16x16x32_bf16 v[124:127], v[172:175], v[232:235], v[124:127]
	v_mfma_f32_16x16x32_bf16 v[112:115], v[164:167], v[240:243], v[112:115]
	v_mfma_f32_16x16x32_bf16 v[108:111], v[172:175], v[240:243], v[108:111]
	v_mfma_f32_16x16x32_bf16 v[160:163], v[168:171], v[220:223], v[160:163]
	v_mfma_f32_16x16x32_bf16 v[156:159], v[176:179], v[220:223], v[156:159]
	v_mfma_f32_16x16x32_bf16 v[144:147], v[168:171], v[228:231], v[144:147]
	v_mfma_f32_16x16x32_bf16 v[140:143], v[176:179], v[228:231], v[140:143]
	v_mfma_f32_16x16x32_bf16 v[128:131], v[168:171], v[236:239], v[128:131]
	v_mfma_f32_16x16x32_bf16 v[124:127], v[176:179], v[236:239], v[124:127]
	v_mfma_f32_16x16x32_bf16 v[112:115], v[168:171], v[244:247], v[112:115]
	v_mfma_f32_16x16x32_bf16 v[108:111], v[176:179], v[244:247], v[108:111]
	s_setprio 0
	s_setprio 1
	v_mfma_f32_16x16x32_bf16 v[152:155], v[192:195], v[216:219], v[152:155]
	v_mfma_f32_16x16x32_bf16 v[148:151], v[204:207], v[216:219], v[148:151]
	v_mfma_f32_16x16x32_bf16 v[136:139], v[192:195], v[224:227], v[136:139]
	v_mfma_f32_16x16x32_bf16 v[132:135], v[204:207], v[224:227], v[132:135]
	v_mfma_f32_16x16x32_bf16 v[120:123], v[192:195], v[232:235], v[120:123]
	v_mfma_f32_16x16x32_bf16 v[116:119], v[204:207], v[232:235], v[116:119]
	v_mfma_f32_16x16x32_bf16 v[104:107], v[192:195], v[240:243], v[104:107]
	v_mfma_f32_16x16x32_bf16 v[100:103], v[204:207], v[240:243], v[100:103]
	v_mfma_f32_16x16x32_bf16 v[152:155], v[196:199], v[220:223], v[152:155]
	v_mfma_f32_16x16x32_bf16 v[148:151], v[210:213], v[220:223], v[148:151]
	v_mfma_f32_16x16x32_bf16 v[136:139], v[196:199], v[228:231], v[136:139]
	v_mfma_f32_16x16x32_bf16 v[132:135], v[210:213], v[228:231], v[132:135]
	v_mfma_f32_16x16x32_bf16 v[120:123], v[196:199], v[236:239], v[120:123]
	v_mfma_f32_16x16x32_bf16 v[116:119], v[210:213], v[236:239], v[116:119]
	v_mfma_f32_16x16x32_bf16 v[104:107], v[196:199], v[244:247], v[104:107]
	v_mfma_f32_16x16x32_bf16 v[100:103], v[210:213], v[244:247], v[100:103]
	s_setprio 0
	s_barrier
	s_add_u32 s34, s52, 0x8000
	s_addc_u32 s35, s53, 0
	s_add_i32 s54, s61, s0
	s_mov_b32 m0, s54
	ds_read_b128 v[216:219], v203 offset:49152
	ds_read_b128 v[220:223], v203 offset:50176
	ds_read_b128 v[224:227], v203 offset:51200
	ds_read_b128 v[228:231], v203 offset:52224
	ds_read_b128 v[232:235], v203 offset:53248
	ds_read_b128 v[236:239], v203 offset:54272
	ds_read_b128 v[240:243], v203 offset:55296
	ds_read_b128 v[244:247], v203 offset:56320
	global_load_lds_dwordx4 v180, s[34:35]
	s_add_i32 m0, s54, 0x2000
	v_lshl_add_u64 v[250:251], s[34:35], 0, v[184:185]
	s_add_u32 s34, s52, 0xc000
	s_addc_u32 s35, s53, 0
	s_add_i32 s52, s62, s0
	global_load_lds_dwordx4 v[250:251], off
	s_mov_b32 m0, s52
	v_lshl_add_u64 v[200:201], v[200:201], 0, s[92:93]
	global_load_lds_dwordx4 v180, s[34:35]
	s_add_i32 m0, s52, 0x2000
	s_nop 0
	global_load_lds_dwordx4 v184, s[34:35]
	s_mov_b32 m0, s91
	s_nop 0
	global_load_lds_dwordx4 v[200:201], off
	v_lshl_add_u64 v[200:201], v[248:249], 0, s[92:93]
	s_mov_b32 m0, s30
	s_nop 0
	global_load_lds_dwordx4 v[200:201], off
	s_waitcnt vmcnt(8)
	s_waitcnt lgkmcnt(0)
	s_barrier
	s_setprio 1
	s_waitcnt lgkmcnt(0)
	v_mfma_f32_16x16x32_bf16 v[96:99], v[164:167], v[216:219], v[96:99]
	v_mfma_f32_16x16x32_bf16 v[92:95], v[172:175], v[216:219], v[92:95]
	v_mfma_f32_16x16x32_bf16 v[84:87], v[164:167], v[224:227], v[84:87]
	v_mfma_f32_16x16x32_bf16 v[76:79], v[172:175], v[224:227], v[76:79]
	v_mfma_f32_16x16x32_bf16 v[68:71], v[164:167], v[232:235], v[68:71]
	v_mfma_f32_16x16x32_bf16 v[60:63], v[172:175], v[232:235], v[60:63]
	v_mfma_f32_16x16x32_bf16 v[52:55], v[164:167], v[240:243], v[52:55]
	v_mfma_f32_16x16x32_bf16 v[44:47], v[172:175], v[240:243], v[44:47]
	v_mfma_f32_16x16x32_bf16 v[96:99], v[168:171], v[220:223], v[96:99]
	v_mfma_f32_16x16x32_bf16 v[92:95], v[176:179], v[220:223], v[92:95]
	v_mfma_f32_16x16x32_bf16 v[84:87], v[168:171], v[228:231], v[84:87]
	v_mfma_f32_16x16x32_bf16 v[76:79], v[176:179], v[228:231], v[76:79]
	v_mfma_f32_16x16x32_bf16 v[68:71], v[168:171], v[236:239], v[68:71]
	v_mfma_f32_16x16x32_bf16 v[60:63], v[176:179], v[236:239], v[60:63]
	v_mfma_f32_16x16x32_bf16 v[52:55], v[168:171], v[244:247], v[52:55]
	v_mfma_f32_16x16x32_bf16 v[44:47], v[176:179], v[244:247], v[44:47]
	s_setprio 0
	s_setprio 1
	v_mfma_f32_16x16x32_bf16 v[88:91], v[192:195], v[216:219], v[88:91]
	v_mfma_f32_16x16x32_bf16 v[80:83], v[204:207], v[216:219], v[80:83]
	v_mfma_f32_16x16x32_bf16 v[72:75], v[192:195], v[224:227], v[72:75]
	v_mfma_f32_16x16x32_bf16 v[64:67], v[204:207], v[224:227], v[64:67]
	v_mfma_f32_16x16x32_bf16 v[56:59], v[192:195], v[232:235], v[56:59]
	v_mfma_f32_16x16x32_bf16 v[48:51], v[204:207], v[232:235], v[48:51]
	v_mfma_f32_16x16x32_bf16 v[40:43], v[192:195], v[240:243], v[40:43]
	v_mfma_f32_16x16x32_bf16 v[36:39], v[204:207], v[240:243], v[36:39]
	v_mfma_f32_16x16x32_bf16 v[88:91], v[196:199], v[220:223], v[88:91]
	v_mfma_f32_16x16x32_bf16 v[80:83], v[210:213], v[220:223], v[80:83]
	v_mfma_f32_16x16x32_bf16 v[72:75], v[196:199], v[228:231], v[72:75]
	v_mfma_f32_16x16x32_bf16 v[64:67], v[210:213], v[228:231], v[64:67]
	v_mfma_f32_16x16x32_bf16 v[56:59], v[196:199], v[236:239], v[56:59]
	v_mfma_f32_16x16x32_bf16 v[48:51], v[210:213], v[236:239], v[48:51]
	v_mfma_f32_16x16x32_bf16 v[40:43], v[196:199], v[244:247], v[40:43]
	v_mfma_f32_16x16x32_bf16 v[36:39], v[210:213], v[244:247], v[36:39]
	s_setprio 0
	s_barrier
	s_add_i32 s60, s60, 2
	s_add_u32 s21, s21, 0x10000
	s_addc_u32 s59, s59, 0
	s_add_u32 s50, s50, 0x100
	s_addc_u32 s51, s51, 0
	s_cmp_gt_u32 s60, 5
	s_cbranch_scc0 .LBB0_707
	s_and_b64 vcc, exec, s[46:47]
	s_cbranch_vccz .LBB0_710
	s_barrier

.LBB0_788:
	s_add_u32 s34, s48, 0xfff80080
	s_addc_u32 s35, s49, -1
	s_add_i32 s57, 0, 0x10000
	s_cmp_eq_u32 s56, 28
	s_cselect_b32 s55, s23, s35
	s_cselect_b32 s54, s22, s34
	v_add_u32_e32 v0, s57, v198
	s_cselect_b32 s53, s43, s51
	s_cselect_b32 s52, s42, s15
	s_add_i32 s69, 0, 0x14000
	ds_read_b128 v[136:139], v0
	ds_read_b128 v[140:143], v0 offset:1024
	ds_read_b128 v[144:147], v0 offset:2048
	ds_read_b128 v[148:151], v0 offset:3072
	v_add_u32_e32 v0, s69, v198
	ds_read_b128 v[152:155], v0
	ds_read_b128 v[156:159], v0 offset:1024
	ds_read_b128 v[160:163], v0 offset:2048
	ds_read_b128 v[174:177], v0 offset:3072
	s_add_i32 m0, s29, 0xc000
	ds_read_b128 v[178:181], v199
	ds_read_b128 v[182:185], v199 offset:1024
	ds_read_b128 v[186:189], v199 offset:2048
	ds_read_b128 v[190:193], v199 offset:3072
	ds_read_b128 v[194:197], v199 offset:4096
	ds_read_b128 v[210:213], v199 offset:5120
	ds_read_b128 v[240:243], v199 offset:6144
	ds_read_b128 v[244:247], v199 offset:7168
	global_load_lds_dwordx4 v170, s[48:49]
	s_add_i32 m0, s29, 0xe000
	s_nop 0
	global_load_lds_dwordx4 v172, s[48:49]
	s_waitcnt vmcnt(8)
	s_waitcnt lgkmcnt(0)
	s_barrier
	s_setprio 1
	s_waitcnt lgkmcnt(0)
	v_mfma_f32_16x16x32_bf16 v[132:135], v[136:139], v[178:181], v[132:135]
	v_mfma_f32_16x16x32_bf16 v[128:131], v[144:147], v[178:181], v[128:131]
	v_mfma_f32_16x16x32_bf16 v[124:127], v[136:139], v[186:189], v[124:127]
	v_mfma_f32_16x16x32_bf16 v[120:123], v[144:147], v[186:189], v[120:123]
	v_mfma_f32_16x16x32_bf16 v[116:119], v[136:139], v[194:197], v[116:119]
	v_mfma_f32_16x16x32_bf16 v[112:115], v[144:147], v[194:197], v[112:115]
	v_mfma_f32_16x16x32_bf16 v[108:111], v[136:139], v[240:243], v[108:111]
	v_mfma_f32_16x16x32_bf16 v[104:107], v[144:147], v[240:243], v[104:107]
	v_mfma_f32_16x16x32_bf16 v[132:135], v[140:143], v[182:185], v[132:135]
	v_mfma_f32_16x16x32_bf16 v[128:131], v[148:151], v[182:185], v[128:131]
	v_mfma_f32_16x16x32_bf16 v[124:127], v[140:143], v[190:193], v[124:127]
	v_mfma_f32_16x16x32_bf16 v[120:123], v[148:151], v[190:193], v[120:123]
	v_mfma_f32_16x16x32_bf16 v[116:119], v[140:143], v[210:213], v[116:119]
	v_mfma_f32_16x16x32_bf16 v[112:115], v[148:151], v[210:213], v[112:115]
	v_mfma_f32_16x16x32_bf16 v[108:111], v[140:143], v[244:247], v[108:111]
	v_mfma_f32_16x16x32_bf16 v[104:107], v[148:151], v[244:247], v[104:107]
	s_setprio 0
	s_setprio 1
	v_mfma_f32_16x16x32_bf16 v[100:103], v[152:155], v[178:181], v[100:103]
	v_mfma_f32_16x16x32_bf16 v[96:99], v[160:163], v[178:181], v[96:99]
	v_mfma_f32_16x16x32_bf16 v[92:95], v[152:155], v[186:189], v[92:95]
	v_mfma_f32_16x16x32_bf16 v[88:91], v[160:163], v[186:189], v[88:91]
	v_mfma_f32_16x16x32_bf16 v[84:87], v[152:155], v[194:197], v[84:87]
	v_mfma_f32_16x16x32_bf16 v[80:83], v[160:163], v[194:197], v[80:83]
	v_mfma_f32_16x16x32_bf16 v[72:75], v[152:155], v[240:243], v[72:75]
	v_mfma_f32_16x16x32_bf16 v[64:67], v[160:163], v[240:243], v[64:67]
	v_mfma_f32_16x16x32_bf16 v[100:103], v[156:159], v[182:185], v[100:103]
	v_mfma_f32_16x16x32_bf16 v[96:99], v[174:177], v[182:185], v[96:99]
	v_mfma_f32_16x16x32_bf16 v[92:95], v[156:159], v[190:193], v[92:95]
	v_mfma_f32_16x16x32_bf16 v[88:91], v[174:177], v[190:193], v[88:91]
	v_mfma_f32_16x16x32_bf16 v[84:87], v[156:159], v[210:213], v[84:87]
	v_mfma_f32_16x16x32_bf16 v[80:83], v[174:177], v[210:213], v[80:83]
	v_mfma_f32_16x16x32_bf16 v[72:75], v[156:159], v[244:247], v[72:75]
	v_mfma_f32_16x16x32_bf16 v[64:67], v[174:177], v[244:247], v[64:67]
	s_setprio 0
	s_barrier
	s_add_i32 s34, s57, s0
	s_mov_b32 m0, s34
	ds_read_b128 v[178:181], v199 offset:16384
	ds_read_b128 v[182:185], v199 offset:17408
	ds_read_b128 v[186:189], v199 offset:18432
	ds_read_b128 v[190:193], v199 offset:19456
	ds_read_b128 v[194:197], v199 offset:20480
	ds_read_b128 v[210:213], v199 offset:21504
	ds_read_b128 v[240:243], v199 offset:22528
	ds_read_b128 v[244:247], v199 offset:23552
	global_load_lds_dwordx4 v32, s[52:53]
	s_add_i32 m0, s34, 0x2000
	s_add_u32 s34, s52, 0x4000
	s_addc_u32 s35, s53, 0
	s_add_i32 s57, s69, s0
	global_load_lds_dwordx4 v166, s[52:53]
	s_mov_b32 m0, s57
	v_lshl_add_u64 v[248:249], s[54:55], 0, v[164:165]
	global_load_lds_dwordx4 v32, s[34:35]
	s_add_i32 m0, s57, 0x2000
	v_lshl_add_u64 v[250:251], s[54:55], 0, v[168:169]
	global_load_lds_dwordx4 v166, s[34:35]
	s_mov_b32 m0, s29
	s_nop 0
	global_load_lds_dwordx4 v164, s[54:55]
	s_mov_b32 m0, s45
	s_nop 0
	global_load_lds_dwordx4 v168, s[54:55]
	s_waitcnt vmcnt(8)
	s_waitcnt lgkmcnt(0)
	s_barrier
	s_setprio 1
	s_waitcnt lgkmcnt(0)
	v_mfma_f32_16x16x32_bf16 v[76:79], v[136:139], v[178:181], v[76:79]
	v_mfma_f32_16x16x32_bf16 v[68:71], v[144:147], v[178:181], v[68:71]
	v_mfma_f32_16x16x32_bf16 v[60:63], v[136:139], v[186:189], v[60:63]
	v_mfma_f32_16x16x32_bf16 v[56:59], v[144:147], v[186:189], v[56:59]
	v_mfma_f32_16x16x32_bf16 v[52:55], v[136:139], v[194:197], v[52:55]
	v_mfma_f32_16x16x32_bf16 v[48:51], v[144:147], v[194:197], v[48:51]
	v_mfma_f32_16x16x32_bf16 v[44:47], v[136:139], v[240:243], v[44:47]
	v_mfma_f32_16x16x32_bf16 v[40:43], v[144:147], v[240:243], v[40:43]
	v_mfma_f32_16x16x32_bf16 v[76:79], v[140:143], v[182:185], v[76:79]
	v_mfma_f32_16x16x32_bf16 v[68:71], v[148:151], v[182:185], v[68:71]
	v_mfma_f32_16x16x32_bf16 v[60:63], v[140:143], v[190:193], v[60:63]
	v_mfma_f32_16x16x32_bf16 v[56:59], v[148:151], v[190:193], v[56:59]
	v_mfma_f32_16x16x32_bf16 v[52:55], v[140:143], v[210:213], v[52:55]
	v_mfma_f32_16x16x32_bf16 v[48:51], v[148:151], v[210:213], v[48:51]
	v_mfma_f32_16x16x32_bf16 v[44:47], v[140:143], v[244:247], v[44:47]
	v_mfma_f32_16x16x32_bf16 v[40:43], v[148:151], v[244:247], v[40:43]
	s_setprio 0
	s_setprio 1
	v_mfma_f32_16x16x32_bf16 v[36:39], v[152:155], v[178:181], v[36:39]
	v_mfma_f32_16x16x32_bf16 v[28:31], v[160:163], v[178:181], v[28:31]
	v_mfma_f32_16x16x32_bf16 v[24:27], v[152:155], v[186:189], v[24:27]
	v_mfma_f32_16x16x32_bf16 v[20:23], v[160:163], v[186:189], v[20:23]
	v_mfma_f32_16x16x32_bf16 v[16:19], v[152:155], v[194:197], v[16:19]
	v_mfma_f32_16x16x32_bf16 v[12:15], v[160:163], v[194:197], v[12:15]
	v_mfma_f32_16x16x32_bf16 v[8:11], v[152:155], v[240:243], v[8:11]
	v_mfma_f32_16x16x32_bf16 v[2:5], v[160:163], v[240:243], v[4:7]
	v_mfma_f32_16x16x32_bf16 v[36:39], v[156:159], v[182:185], v[36:39]
	v_mfma_f32_16x16x32_bf16 v[28:31], v[174:177], v[182:185], v[28:31]
	v_mfma_f32_16x16x32_bf16 v[24:27], v[156:159], v[190:193], v[24:27]
	v_mfma_f32_16x16x32_bf16 v[20:23], v[174:177], v[190:193], v[20:23]
	v_mfma_f32_16x16x32_bf16 v[16:19], v[156:159], v[210:213], v[16:19]
	v_mfma_f32_16x16x32_bf16 v[12:15], v[174:177], v[210:213], v[12:15]
	v_mfma_f32_16x16x32_bf16 v[8:11], v[156:159], v[244:247], v[8:11]
	v_mfma_f32_16x16x32_bf16 v[2:5], v[174:177], v[244:247], v[2:5]
	s_setprio 0
	s_barrier
	s_add_i32 s57, 0, 0x18000
	v_add_u32_e32 v0, s57, v198
	s_add_i32 s69, 0, 0x1c000
	ds_read_b128 v[136:139], v0
	ds_read_b128 v[140:143], v0 offset:1024
	ds_read_b128 v[144:147], v0 offset:2048
	ds_read_b128 v[148:151], v0 offset:3072
	v_add_u32_e32 v0, s69, v198
	ds_read_b128 v[152:155], v0
	ds_read_b128 v[156:159], v0 offset:1024
	ds_read_b128 v[160:163], v0 offset:2048
	ds_read_b128 v[174:177], v0 offset:3072
	s_add_u32 s34, s54, 0x80000
	s_addc_u32 s35, s55, 0
	s_mov_b32 m0, s82
	ds_read_b128 v[178:181], v199 offset:32768
	ds_read_b128 v[182:185], v199 offset:33792
	ds_read_b128 v[186:189], v199 offset:34816
	ds_read_b128 v[190:193], v199 offset:35840
	ds_read_b128 v[194:197], v199 offset:36864
	ds_read_b128 v[210:213], v199 offset:37888
	ds_read_b128 v[240:243], v199 offset:38912
	ds_read_b128 v[244:247], v199 offset:39936
	global_load_lds_dwordx4 v164, s[34:35]
	s_mov_b32 m0, s90
	s_nop 0
	global_load_lds_dwordx4 v168, s[34:35]
	s_waitcnt vmcnt(8)
	s_waitcnt lgkmcnt(0)
	s_barrier
	s_setprio 1
	s_waitcnt lgkmcnt(0)
	v_mfma_f32_16x16x32_bf16 v[132:135], v[136:139], v[178:181], v[132:135]
	v_mfma_f32_16x16x32_bf16 v[128:131], v[144:147], v[178:181], v[128:131]
	v_mfma_f32_16x16x32_bf16 v[124:127], v[136:139], v[186:189], v[124:127]
	v_mfma_f32_16x16x32_bf16 v[120:123], v[144:147], v[186:189], v[120:123]
	v_mfma_f32_16x16x32_bf16 v[116:119], v[136:139], v[194:197], v[116:119]
	v_mfma_f32_16x16x32_bf16 v[112:115], v[144:147], v[194:197], v[112:115]
	v_mfma_f32_16x16x32_bf16 v[108:111], v[136:139], v[240:243], v[108:111]
	v_mfma_f32_16x16x32_bf16 v[104:107], v[144:147], v[240:243], v[104:107]
	v_mfma_f32_16x16x32_bf16 v[132:135], v[140:143], v[182:185], v[132:135]
	v_mfma_f32_16x16x32_bf16 v[128:131], v[148:151], v[182:185], v[128:131]
	v_mfma_f32_16x16x32_bf16 v[124:127], v[140:143], v[190:193], v[124:127]
	v_mfma_f32_16x16x32_bf16 v[120:123], v[148:151], v[190:193], v[120:123]
	v_mfma_f32_16x16x32_bf16 v[116:119], v[140:143], v[210:213], v[116:119]
	v_mfma_f32_16x16x32_bf16 v[112:115], v[148:151], v[210:213], v[112:115]
	v_mfma_f32_16x16x32_bf16 v[108:111], v[140:143], v[244:247], v[108:111]
	v_mfma_f32_16x16x32_bf16 v[104:107], v[148:151], v[244:247], v[104:107]
	s_setprio 0
	s_setprio 1
	v_mfma_f32_16x16x32_bf16 v[100:103], v[152:155], v[178:181], v[100:103]
	v_mfma_f32_16x16x32_bf16 v[96:99], v[160:163], v[178:181], v[96:99]
	v_mfma_f32_16x16x32_bf16 v[92:95], v[152:155], v[186:189], v[92:95]
	v_mfma_f32_16x16x32_bf16 v[88:91], v[160:163], v[186:189], v[88:91]
	v_mfma_f32_16x16x32_bf16 v[84:87], v[152:155], v[194:197], v[84:87]
	v_mfma_f32_16x16x32_bf16 v[80:83], v[160:163], v[194:197], v[80:83]
	v_mfma_f32_16x16x32_bf16 v[72:75], v[152:155], v[240:243], v[72:75]
	v_mfma_f32_16x16x32_bf16 v[64:67], v[160:163], v[240:243], v[64:67]
	v_mfma_f32_16x16x32_bf16 v[100:103], v[156:159], v[182:185], v[100:103]
	v_mfma_f32_16x16x32_bf16 v[96:99], v[174:177], v[182:185], v[96:99]
	v_mfma_f32_16x16x32_bf16 v[92:95], v[156:159], v[190:193], v[92:95]
	v_mfma_f32_16x16x32_bf16 v[88:91], v[174:177], v[190:193], v[88:91]
	v_mfma_f32_16x16x32_bf16 v[84:87], v[156:159], v[210:213], v[84:87]
	v_mfma_f32_16x16x32_bf16 v[80:83], v[174:177], v[210:213], v[80:83]
	v_mfma_f32_16x16x32_bf16 v[72:75], v[156:159], v[244:247], v[72:75]
	v_mfma_f32_16x16x32_bf16 v[64:67], v[174:177], v[244:247], v[64:67]
	s_setprio 0
	s_barrier
	s_add_u32 s34, s52, 0x8000
	s_addc_u32 s35, s53, 0
	s_add_i32 s54, s57, s0
	s_mov_b32 m0, s54
	ds_read_b128 v[178:181], v199 offset:49152
	ds_read_b128 v[182:185], v199 offset:50176
	ds_read_b128 v[186:189], v199 offset:51200
	ds_read_b128 v[190:193], v199 offset:52224
	ds_read_b128 v[194:197], v199 offset:53248
	ds_read_b128 v[210:213], v199 offset:54272
	ds_read_b128 v[240:243], v199 offset:55296
	ds_read_b128 v[244:247], v199 offset:56320
	global_load_lds_dwordx4 v32, s[34:35]
	s_add_i32 m0, s54, 0x2000
	v_lshl_add_u64 v[6:7], s[34:35], 0, v[166:167]
	s_add_u32 s34, s52, 0xc000
	s_addc_u32 s35, s53, 0
	s_add_i32 s52, s69, s0
	global_load_lds_dwordx4 v[6:7], off
	s_mov_b32 m0, s52
	s_nop 0
	global_load_lds_dwordx4 v32, s[34:35]
	s_add_i32 m0, s52, 0x2000
	s_nop 0
	global_load_lds_dwordx4 v166, s[34:35]
	v_lshl_add_u64 v[6:7], v[248:249], 0, s[92:93]
	s_mov_b32 m0, s91
	s_nop 0
	global_load_lds_dwordx4 v[6:7], off
	v_lshl_add_u64 v[6:7], v[250:251], 0, s[92:93]
	s_mov_b32 m0, s30
	s_nop 0
	global_load_lds_dwordx4 v[6:7], off
	s_waitcnt vmcnt(8)
	s_waitcnt lgkmcnt(0)
	s_barrier
	s_setprio 1
	s_waitcnt lgkmcnt(0)
	v_mfma_f32_16x16x32_bf16 v[76:79], v[136:139], v[178:181], v[76:79]
	v_mfma_f32_16x16x32_bf16 v[68:71], v[144:147], v[178:181], v[68:71]
	v_mfma_f32_16x16x32_bf16 v[60:63], v[136:139], v[186:189], v[60:63]
	v_mfma_f32_16x16x32_bf16 v[56:59], v[144:147], v[186:189], v[56:59]
	v_mfma_f32_16x16x32_bf16 v[52:55], v[136:139], v[194:197], v[52:55]
	v_mfma_f32_16x16x32_bf16 v[48:51], v[144:147], v[194:197], v[48:51]
	v_mfma_f32_16x16x32_bf16 v[44:47], v[136:139], v[240:243], v[44:47]
	v_mfma_f32_16x16x32_bf16 v[40:43], v[144:147], v[240:243], v[40:43]
	v_mfma_f32_16x16x32_bf16 v[76:79], v[140:143], v[182:185], v[76:79]
	v_mfma_f32_16x16x32_bf16 v[68:71], v[148:151], v[182:185], v[68:71]
	v_mfma_f32_16x16x32_bf16 v[60:63], v[140:143], v[190:193], v[60:63]
	v_mfma_f32_16x16x32_bf16 v[56:59], v[148:151], v[190:193], v[56:59]
	v_mfma_f32_16x16x32_bf16 v[52:55], v[140:143], v[210:213], v[52:55]
	v_mfma_f32_16x16x32_bf16 v[48:51], v[148:151], v[210:213], v[48:51]
	v_mfma_f32_16x16x32_bf16 v[44:47], v[140:143], v[244:247], v[44:47]
	v_mfma_f32_16x16x32_bf16 v[40:43], v[148:151], v[244:247], v[40:43]
	s_setprio 0
	s_setprio 1
	v_mfma_f32_16x16x32_bf16 v[36:39], v[152:155], v[178:181], v[36:39]
	v_mfma_f32_16x16x32_bf16 v[28:31], v[160:163], v[178:181], v[28:31]
	v_mfma_f32_16x16x32_bf16 v[24:27], v[152:155], v[186:189], v[24:27]
	v_mfma_f32_16x16x32_bf16 v[20:23], v[160:163], v[186:189], v[20:23]
	v_mfma_f32_16x16x32_bf16 v[16:19], v[152:155], v[194:197], v[16:19]
	v_mfma_f32_16x16x32_bf16 v[12:15], v[160:163], v[194:197], v[12:15]
	v_mfma_f32_16x16x32_bf16 v[6:9], v[152:155], v[240:243], v[8:11]
	v_mfma_f32_16x16x32_bf16 v[2:5], v[160:163], v[240:243], v[2:5]
	v_mfma_f32_16x16x32_bf16 v[36:39], v[156:159], v[182:185], v[36:39]
	v_mfma_f32_16x16x32_bf16 v[28:31], v[174:177], v[182:185], v[28:31]
	v_mfma_f32_16x16x32_bf16 v[24:27], v[156:159], v[190:193], v[24:27]
	v_mfma_f32_16x16x32_bf16 v[20:23], v[174:177], v[190:193], v[20:23]
	v_mfma_f32_16x16x32_bf16 v[16:19], v[156:159], v[210:213], v[16:19]
	v_mfma_f32_16x16x32_bf16 v[12:15], v[174:177], v[210:213], v[12:15]
	v_mfma_f32_16x16x32_bf16 v[8:11], v[156:159], v[244:247], v[6:9]
	v_mfma_f32_16x16x32_bf16 v[4:7], v[174:177], v[244:247], v[2:5]
	s_setprio 0
	s_barrier
	s_add_i32 s56, s56, 2
	s_add_u32 s15, s15, 0x10000
	s_addc_u32 s51, s51, 0
	s_add_u32 s48, s48, 0x100
	s_addc_u32 s49, s49, 0
	s_cmp_gt_u32 s56, 29
	s_cbranch_scc0 .LBB0_788
	s_and_b64 vcc, exec, s[46:47]
	s_cbranch_vccz .LBB0_791
	s_barrier

.LBB0_877:
	s_add_u32 s62, s60, 0x100
	s_addc_u32 s63, s61, 0
	s_add_i32 s34, 0, 0x10000
	s_cmp_eq_u32 s49, 60
	s_cselect_b32 s67, s51, s63
	s_cselect_b32 s66, s50, s62
	v_add_u32_e32 v0, s34, v188
	s_cselect_b32 s65, s53, s28
	s_cselect_b32 s64, s52, s13
	s_add_i32 s55, 0, 0x14000
	ds_read_b128 v[132:135], v0
	ds_read_b128 v[136:139], v0 offset:1024
	ds_read_b128 v[140:143], v0 offset:2048
	ds_read_b128 v[144:147], v0 offset:3072
	v_add_u32_e32 v0, s55, v188
	ds_read_b128 v[148:151], v0
	ds_read_b128 v[152:155], v0 offset:1024
	ds_read_b128 v[168:171], v0 offset:2048
	ds_read_b128 v[172:175], v0 offset:3072
	s_add_i32 m0, s29, 0xc000
	ds_read_b128 v[176:179], v189
	ds_read_b128 v[180:183], v189 offset:1024
	ds_read_b128 v[184:187], v189 offset:2048
	ds_read_b128 v[192:195], v189 offset:3072
	ds_read_b128 v[210:213], v189 offset:4096
	ds_read_b128 v[234:237], v189 offset:5120
	ds_read_b128 v[238:241], v189 offset:6144
	ds_read_b128 v[242:245], v189 offset:7168
	global_load_lds_dwordx4 v164, s[60:61]
	s_add_i32 m0, s29, 0xe000
	s_nop 0
	global_load_lds_dwordx4 v166, s[60:61]
	s_waitcnt vmcnt(8)
	s_waitcnt lgkmcnt(0)
	s_barrier
	s_setprio 1
	s_waitcnt lgkmcnt(0)
	v_mfma_f32_16x16x32_bf16 v[128:131], v[132:135], v[176:179], v[128:131]
	v_mfma_f32_16x16x32_bf16 v[124:127], v[140:143], v[176:179], v[124:127]
	v_mfma_f32_16x16x32_bf16 v[112:115], v[132:135], v[184:187], v[112:115]
	v_mfma_f32_16x16x32_bf16 v[108:111], v[140:143], v[184:187], v[108:111]
	v_mfma_f32_16x16x32_bf16 v[96:99], v[132:135], v[210:213], v[96:99]
	v_mfma_f32_16x16x32_bf16 v[92:95], v[140:143], v[210:213], v[92:95]
	v_mfma_f32_16x16x32_bf16 v[80:83], v[132:135], v[238:241], v[80:83]
	v_mfma_f32_16x16x32_bf16 v[76:79], v[140:143], v[238:241], v[76:79]
	v_mfma_f32_16x16x32_bf16 v[128:131], v[136:139], v[180:183], v[128:131]
	v_mfma_f32_16x16x32_bf16 v[124:127], v[144:147], v[180:183], v[124:127]
	v_mfma_f32_16x16x32_bf16 v[112:115], v[136:139], v[192:195], v[112:115]
	v_mfma_f32_16x16x32_bf16 v[108:111], v[144:147], v[192:195], v[108:111]
	v_mfma_f32_16x16x32_bf16 v[96:99], v[136:139], v[234:237], v[96:99]
	v_mfma_f32_16x16x32_bf16 v[92:95], v[144:147], v[234:237], v[92:95]
	v_mfma_f32_16x16x32_bf16 v[80:83], v[136:139], v[242:245], v[80:83]
	v_mfma_f32_16x16x32_bf16 v[76:79], v[144:147], v[242:245], v[76:79]
	s_setprio 0
	s_setprio 1
	v_mfma_f32_16x16x32_bf16 v[120:123], v[148:151], v[176:179], v[120:123]
	v_mfma_f32_16x16x32_bf16 v[116:119], v[168:171], v[176:179], v[116:119]
	v_mfma_f32_16x16x32_bf16 v[104:107], v[148:151], v[184:187], v[104:107]
	v_mfma_f32_16x16x32_bf16 v[100:103], v[168:171], v[184:187], v[100:103]
	v_mfma_f32_16x16x32_bf16 v[88:91], v[148:151], v[210:213], v[88:91]
	v_mfma_f32_16x16x32_bf16 v[84:87], v[168:171], v[210:213], v[84:87]
	v_mfma_f32_16x16x32_bf16 v[72:75], v[148:151], v[238:241], v[72:75]
	v_mfma_f32_16x16x32_bf16 v[68:71], v[168:171], v[238:241], v[68:71]
	v_mfma_f32_16x16x32_bf16 v[120:123], v[152:155], v[180:183], v[120:123]
	v_mfma_f32_16x16x32_bf16 v[116:119], v[172:175], v[180:183], v[116:119]
	v_mfma_f32_16x16x32_bf16 v[104:107], v[152:155], v[192:195], v[104:107]
	v_mfma_f32_16x16x32_bf16 v[100:103], v[172:175], v[192:195], v[100:103]
	v_mfma_f32_16x16x32_bf16 v[88:91], v[152:155], v[234:237], v[88:91]
	v_mfma_f32_16x16x32_bf16 v[84:87], v[172:175], v[234:237], v[84:87]
	v_mfma_f32_16x16x32_bf16 v[72:75], v[152:155], v[242:245], v[72:75]
	v_mfma_f32_16x16x32_bf16 v[68:71], v[172:175], v[242:245], v[68:71]
	s_setprio 0
	s_barrier
	s_add_i32 s34, s34, s0
	s_mov_b32 m0, s34
	ds_read_b128 v[176:179], v189 offset:16384
	ds_read_b128 v[180:183], v189 offset:17408
	ds_read_b128 v[184:187], v189 offset:18432
	ds_read_b128 v[192:195], v189 offset:19456
	ds_read_b128 v[210:213], v189 offset:20480
	ds_read_b128 v[234:237], v189 offset:21504
	ds_read_b128 v[238:241], v189 offset:22528
	ds_read_b128 v[242:245], v189 offset:23552
	global_load_lds_dwordx4 v156, s[64:65]
	s_add_i32 m0, s34, 0x2000
	s_add_u32 s34, s64, 0x4000
	s_addc_u32 s35, s65, 0
	s_add_i32 s55, s55, s0
	global_load_lds_dwordx4 v160, s[64:65]
	s_mov_b32 m0, s55
	s_nop 0
	global_load_lds_dwordx4 v156, s[34:35]
	s_add_i32 m0, s55, 0x2000
	s_nop 0
	global_load_lds_dwordx4 v160, s[34:35]
	s_mov_b32 m0, s29
	s_nop 0
	global_load_lds_dwordx4 v158, s[66:67]
	s_mov_b32 m0, s45
	s_nop 0
	global_load_lds_dwordx4 v162, s[66:67]
	s_waitcnt vmcnt(8)
	s_waitcnt lgkmcnt(0)
	s_barrier
	s_setprio 1
	s_waitcnt lgkmcnt(0)
	v_mfma_f32_16x16x32_bf16 v[64:67], v[132:135], v[176:179], v[64:67]
	v_mfma_f32_16x16x32_bf16 v[60:63], v[140:143], v[176:179], v[60:63]
	v_mfma_f32_16x16x32_bf16 v[48:51], v[132:135], v[184:187], v[48:51]
	v_mfma_f32_16x16x32_bf16 v[44:47], v[140:143], v[184:187], v[44:47]
	v_mfma_f32_16x16x32_bf16 v[30:33], v[132:135], v[210:213], v[30:33]
	v_mfma_f32_16x16x32_bf16 v[26:29], v[140:143], v[210:213], v[26:29]
	v_mfma_f32_16x16x32_bf16 v[14:17], v[132:135], v[238:241], v[14:17]
	v_mfma_f32_16x16x32_bf16 v[10:13], v[140:143], v[238:241], v[10:13]
	v_mfma_f32_16x16x32_bf16 v[64:67], v[136:139], v[180:183], v[64:67]
	v_mfma_f32_16x16x32_bf16 v[60:63], v[144:147], v[180:183], v[60:63]
	v_mfma_f32_16x16x32_bf16 v[48:51], v[136:139], v[192:195], v[48:51]
	v_mfma_f32_16x16x32_bf16 v[44:47], v[144:147], v[192:195], v[44:47]
	v_mfma_f32_16x16x32_bf16 v[30:33], v[136:139], v[234:237], v[30:33]
	v_mfma_f32_16x16x32_bf16 v[26:29], v[144:147], v[234:237], v[26:29]
	v_mfma_f32_16x16x32_bf16 v[14:17], v[136:139], v[242:245], v[14:17]
	v_mfma_f32_16x16x32_bf16 v[10:13], v[144:147], v[242:245], v[10:13]
	s_setprio 0
	s_setprio 1
	v_mfma_f32_16x16x32_bf16 v[56:59], v[148:151], v[176:179], v[56:59]
	v_mfma_f32_16x16x32_bf16 v[52:55], v[168:171], v[176:179], v[52:55]
	v_mfma_f32_16x16x32_bf16 v[40:43], v[148:151], v[184:187], v[40:43]
	v_mfma_f32_16x16x32_bf16 v[36:39], v[168:171], v[184:187], v[36:39]
	v_mfma_f32_16x16x32_bf16 v[22:25], v[148:151], v[210:213], v[22:25]
	v_mfma_f32_16x16x32_bf16 v[18:21], v[168:171], v[210:213], v[18:21]
	v_mfma_f32_16x16x32_bf16 v[6:9], v[148:151], v[238:241], v[6:9]
	v_mfma_f32_16x16x32_bf16 v[2:5], v[168:171], v[238:241], v[2:5]
	v_mfma_f32_16x16x32_bf16 v[56:59], v[152:155], v[180:183], v[56:59]
	v_mfma_f32_16x16x32_bf16 v[52:55], v[172:175], v[180:183], v[52:55]
	v_mfma_f32_16x16x32_bf16 v[40:43], v[152:155], v[192:195], v[40:43]
	v_mfma_f32_16x16x32_bf16 v[36:39], v[172:175], v[192:195], v[36:39]
	v_mfma_f32_16x16x32_bf16 v[22:25], v[152:155], v[234:237], v[22:25]
	v_mfma_f32_16x16x32_bf16 v[18:21], v[172:175], v[234:237], v[18:21]
	v_mfma_f32_16x16x32_bf16 v[6:9], v[152:155], v[242:245], v[6:9]
	v_mfma_f32_16x16x32_bf16 v[2:5], v[172:175], v[242:245], v[2:5]
	s_setprio 0
	s_barrier
	s_add_i32 s55, 0, 0x18000
	v_add_u32_e32 v0, s55, v188
	s_add_i32 s58, 0, 0x1c000
	ds_read_b128 v[132:135], v0
	ds_read_b128 v[136:139], v0 offset:1024
	ds_read_b128 v[140:143], v0 offset:2048
	ds_read_b128 v[144:147], v0 offset:3072
	v_add_u32_e32 v0, s58, v188
	ds_read_b128 v[148:151], v0
	ds_read_b128 v[152:155], v0 offset:1024
	ds_read_b128 v[168:171], v0 offset:2048
	ds_read_b128 v[172:175], v0 offset:3072
	s_add_u32 s34, s66, 0x100000
	s_addc_u32 s35, s67, 0
	s_mov_b32 m0, s82
	ds_read_b128 v[176:179], v189 offset:32768
	ds_read_b128 v[180:183], v189 offset:33792
	ds_read_b128 v[184:187], v189 offset:34816
	ds_read_b128 v[192:195], v189 offset:35840
	ds_read_b128 v[210:213], v189 offset:36864
	ds_read_b128 v[234:237], v189 offset:37888
	ds_read_b128 v[238:241], v189 offset:38912
	ds_read_b128 v[242:245], v189 offset:39936
	global_load_lds_dwordx4 v158, s[34:35]
	s_mov_b32 m0, s90
	s_nop 0
	global_load_lds_dwordx4 v162, s[34:35]
	s_waitcnt vmcnt(8)
	s_waitcnt lgkmcnt(0)
	s_barrier
	s_setprio 1
	s_waitcnt lgkmcnt(0)
	v_mfma_f32_16x16x32_bf16 v[128:131], v[132:135], v[176:179], v[128:131]
	v_mfma_f32_16x16x32_bf16 v[124:127], v[140:143], v[176:179], v[124:127]
	v_mfma_f32_16x16x32_bf16 v[112:115], v[132:135], v[184:187], v[112:115]
	v_mfma_f32_16x16x32_bf16 v[108:111], v[140:143], v[184:187], v[108:111]
	v_mfma_f32_16x16x32_bf16 v[96:99], v[132:135], v[210:213], v[96:99]
	v_mfma_f32_16x16x32_bf16 v[92:95], v[140:143], v[210:213], v[92:95]
	v_mfma_f32_16x16x32_bf16 v[80:83], v[132:135], v[238:241], v[80:83]
	v_mfma_f32_16x16x32_bf16 v[76:79], v[140:143], v[238:241], v[76:79]
	v_mfma_f32_16x16x32_bf16 v[128:131], v[136:139], v[180:183], v[128:131]
	v_mfma_f32_16x16x32_bf16 v[124:127], v[144:147], v[180:183], v[124:127]
	v_mfma_f32_16x16x32_bf16 v[112:115], v[136:139], v[192:195], v[112:115]
	v_mfma_f32_16x16x32_bf16 v[108:111], v[144:147], v[192:195], v[108:111]
	v_mfma_f32_16x16x32_bf16 v[96:99], v[136:139], v[234:237], v[96:99]
	v_mfma_f32_16x16x32_bf16 v[92:95], v[144:147], v[234:237], v[92:95]
	v_mfma_f32_16x16x32_bf16 v[80:83], v[136:139], v[242:245], v[80:83]
	v_mfma_f32_16x16x32_bf16 v[76:79], v[144:147], v[242:245], v[76:79]
	s_setprio 0
	s_setprio 1
	v_mfma_f32_16x16x32_bf16 v[120:123], v[148:151], v[176:179], v[120:123]
	v_mfma_f32_16x16x32_bf16 v[116:119], v[168:171], v[176:179], v[116:119]
	v_mfma_f32_16x16x32_bf16 v[104:107], v[148:151], v[184:187], v[104:107]
	v_mfma_f32_16x16x32_bf16 v[100:103], v[168:171], v[184:187], v[100:103]
	v_mfma_f32_16x16x32_bf16 v[88:91], v[148:151], v[210:213], v[88:91]
	v_mfma_f32_16x16x32_bf16 v[84:87], v[168:171], v[210:213], v[84:87]
	v_mfma_f32_16x16x32_bf16 v[72:75], v[148:151], v[238:241], v[72:75]
	v_mfma_f32_16x16x32_bf16 v[68:71], v[168:171], v[238:241], v[68:71]
	v_mfma_f32_16x16x32_bf16 v[120:123], v[152:155], v[180:183], v[120:123]
	v_mfma_f32_16x16x32_bf16 v[116:119], v[172:175], v[180:183], v[116:119]
	v_mfma_f32_16x16x32_bf16 v[104:107], v[152:155], v[192:195], v[104:107]
	v_mfma_f32_16x16x32_bf16 v[100:103], v[172:175], v[192:195], v[100:103]
	v_mfma_f32_16x16x32_bf16 v[88:91], v[152:155], v[234:237], v[88:91]
	v_mfma_f32_16x16x32_bf16 v[84:87], v[172:175], v[234:237], v[84:87]
	v_mfma_f32_16x16x32_bf16 v[72:75], v[152:155], v[242:245], v[72:75]
	v_mfma_f32_16x16x32_bf16 v[68:71], v[172:175], v[242:245], v[68:71]
	s_setprio 0
	s_barrier
	s_add_u32 s34, s64, 0x8000
	s_addc_u32 s35, s65, 0
	s_add_i32 s55, s55, s0
	s_mov_b32 m0, s55
	ds_read_b128 v[176:179], v189 offset:49152
	ds_read_b128 v[180:183], v189 offset:50176
	ds_read_b128 v[184:187], v189 offset:51200
	ds_read_b128 v[192:195], v189 offset:52224
	ds_read_b128 v[210:213], v189 offset:53248
	ds_read_b128 v[234:237], v189 offset:54272
	ds_read_b128 v[238:241], v189 offset:55296
	ds_read_b128 v[242:245], v189 offset:56320
	global_load_lds_dwordx4 v156, s[34:35]
	s_add_i32 m0, s55, 0x2000
	v_lshl_add_u64 v[250:251], s[34:35], 0, v[160:161]
	s_add_u32 s34, s64, 0xc000
	s_addc_u32 s35, s65, 0
	s_add_i32 s55, s58, s0
	global_load_lds_dwordx4 v[250:251], off
	s_mov_b32 m0, s55
	s_nop 0
	global_load_lds_dwordx4 v156, s[34:35]
	s_add_i32 m0, s55, 0x2000
	s_nop 0
	global_load_lds_dwordx4 v160, s[34:35]
	s_mov_b32 m0, s91
	s_nop 0
	s_add_u32 s100, s66, s92
	s_addc_u32 s101, s67, s93
	global_load_lds_dwordx4 v158, s[100:101]
	s_mov_b32 m0, s30
	s_nop 0
	s_add_u32 s100, s66, s92
	s_addc_u32 s101, s67, s93
	global_load_lds_dwordx4 v162, s[100:101]
	s_waitcnt vmcnt(8)
	s_waitcnt lgkmcnt(0)
	s_barrier
	s_setprio 1
	s_waitcnt lgkmcnt(0)
	v_mfma_f32_16x16x32_bf16 v[64:67], v[132:135], v[176:179], v[64:67]
	v_mfma_f32_16x16x32_bf16 v[60:63], v[140:143], v[176:179], v[60:63]
	v_mfma_f32_16x16x32_bf16 v[48:51], v[132:135], v[184:187], v[48:51]
	v_mfma_f32_16x16x32_bf16 v[44:47], v[140:143], v[184:187], v[44:47]
	v_mfma_f32_16x16x32_bf16 v[30:33], v[132:135], v[210:213], v[30:33]
	v_mfma_f32_16x16x32_bf16 v[26:29], v[140:143], v[210:213], v[26:29]
	v_mfma_f32_16x16x32_bf16 v[14:17], v[132:135], v[238:241], v[14:17]
	v_mfma_f32_16x16x32_bf16 v[10:13], v[140:143], v[238:241], v[10:13]
	v_mfma_f32_16x16x32_bf16 v[64:67], v[136:139], v[180:183], v[64:67]
	v_mfma_f32_16x16x32_bf16 v[60:63], v[144:147], v[180:183], v[60:63]
	v_mfma_f32_16x16x32_bf16 v[48:51], v[136:139], v[192:195], v[48:51]
	v_mfma_f32_16x16x32_bf16 v[44:47], v[144:147], v[192:195], v[44:47]
	v_mfma_f32_16x16x32_bf16 v[30:33], v[136:139], v[234:237], v[30:33]
	v_mfma_f32_16x16x32_bf16 v[26:29], v[144:147], v[234:237], v[26:29]
	v_mfma_f32_16x16x32_bf16 v[14:17], v[136:139], v[242:245], v[14:17]
	v_mfma_f32_16x16x32_bf16 v[10:13], v[144:147], v[242:245], v[10:13]
	s_setprio 0
	s_setprio 1
	v_mfma_f32_16x16x32_bf16 v[56:59], v[148:151], v[176:179], v[56:59]
	v_mfma_f32_16x16x32_bf16 v[52:55], v[168:171], v[176:179], v[52:55]
	v_mfma_f32_16x16x32_bf16 v[40:43], v[148:151], v[184:187], v[40:43]
	v_mfma_f32_16x16x32_bf16 v[36:39], v[168:171], v[184:187], v[36:39]
	v_mfma_f32_16x16x32_bf16 v[22:25], v[148:151], v[210:213], v[22:25]
	v_mfma_f32_16x16x32_bf16 v[18:21], v[168:171], v[210:213], v[18:21]
	v_mfma_f32_16x16x32_bf16 v[6:9], v[148:151], v[238:241], v[6:9]
	v_mfma_f32_16x16x32_bf16 v[2:5], v[168:171], v[238:241], v[2:5]
	v_mfma_f32_16x16x32_bf16 v[56:59], v[152:155], v[180:183], v[56:59]
	v_mfma_f32_16x16x32_bf16 v[52:55], v[172:175], v[180:183], v[52:55]
	v_mfma_f32_16x16x32_bf16 v[40:43], v[152:155], v[192:195], v[40:43]
	v_mfma_f32_16x16x32_bf16 v[36:39], v[172:175], v[192:195], v[36:39]
	v_mfma_f32_16x16x32_bf16 v[22:25], v[152:155], v[234:237], v[22:25]
	v_mfma_f32_16x16x32_bf16 v[18:21], v[172:175], v[234:237], v[18:21]
	v_mfma_f32_16x16x32_bf16 v[6:9], v[152:155], v[242:245], v[6:9]
	v_mfma_f32_16x16x32_bf16 v[2:5], v[172:175], v[242:245], v[2:5]
	s_setprio 0
	s_barrier
	s_add_i32 s49, s49, 2
	s_add_u32 s13, s13, 0x10000
	s_addc_u32 s28, s28, 0
	s_cmp_gt_u32 s49, 61
	s_mov_b64 s[60:61], s[62:63]
	s_cbranch_scc0 .LBB0_877
	s_and_b64 vcc, exec, s[46:47]
	s_cbranch_vccz .LBB0_880
	s_barrier

.LBB0_1070:
	s_add_u32 s34, s12, 0xfff00080
	s_addc_u32 s35, s13, -1
	s_add_i32 s48, 0, 0x10000
	s_cmp_eq_u32 s59, 28
	s_cselect_b32 s67, s61, s35
	s_cselect_b32 s66, s60, s34
	v_add_u32_e32 v0, s48, v196
	s_cselect_b32 s65, s63, s58
	s_cselect_b32 s64, s62, s28
	s_add_i32 s49, 0, 0x14000
	ds_read_b128 v[100:103], v0
	ds_read_b128 v[112:115], v0 offset:1024
	ds_read_b128 v[172:175], v0 offset:2048
	ds_read_b128 v[188:191], v0 offset:3072
	v_add_u32_e32 v0, s49, v196
	ds_read_b128 v[192:195], v0
	ds_read_b128 v[200:203], v0 offset:1024
	ds_read_b128 v[204:207], v0 offset:2048
	ds_read_b128 v[210:213], v0 offset:3072
	s_add_i32 m0, s29, 0xc000
	ds_read_b128 v[216:219], v197
	ds_read_b128 v[220:223], v197 offset:1024
	ds_read_b128 v[224:227], v197 offset:2048
	ds_read_b128 v[228:231], v197 offset:3072
	ds_read_b128 v[232:235], v197 offset:4096
	ds_read_b128 v[236:239], v197 offset:5120
	ds_read_b128 v[240:243], v197 offset:6144
	ds_read_b128 v[244:247], v197 offset:7168
	global_load_lds_dwordx4 v184, s[12:13]
	s_add_i32 m0, s29, 0xe000
	s_nop 0
	global_load_lds_dwordx4 v186, s[12:13]
	s_waitcnt vmcnt(8)
	s_waitcnt lgkmcnt(0)
	s_barrier
	s_setprio 1
	s_waitcnt lgkmcnt(0)
	v_mfma_i32_16x16x64_i8 v[168:171], v[100:103], v[216:219], v[168:171]
	v_mfma_i32_16x16x64_i8 v[160:163], v[172:175], v[216:219], v[160:163]
	v_mfma_i32_16x16x64_i8 v[152:155], v[100:103], v[224:227], v[152:155]
	v_mfma_i32_16x16x64_i8 v[144:147], v[172:175], v[224:227], v[144:147]
	v_mfma_i32_16x16x64_i8 v[136:139], v[100:103], v[232:235], v[136:139]
	v_mfma_i32_16x16x64_i8 v[128:131], v[172:175], v[232:235], v[128:131]
	v_mfma_i32_16x16x64_i8 v[120:123], v[100:103], v[240:243], v[120:123]
	v_mfma_i32_16x16x64_i8 v[108:111], v[172:175], v[240:243], v[108:111]
	v_mfma_i32_16x16x64_i8 v[168:171], v[112:115], v[220:223], v[168:171]
	v_mfma_i32_16x16x64_i8 v[160:163], v[188:191], v[220:223], v[160:163]
	v_mfma_i32_16x16x64_i8 v[152:155], v[112:115], v[228:231], v[152:155]
	v_mfma_i32_16x16x64_i8 v[144:147], v[188:191], v[228:231], v[144:147]
	v_mfma_i32_16x16x64_i8 v[136:139], v[112:115], v[236:239], v[136:139]
	v_mfma_i32_16x16x64_i8 v[128:131], v[188:191], v[236:239], v[128:131]
	v_mfma_i32_16x16x64_i8 v[120:123], v[112:115], v[244:247], v[120:123]
	v_mfma_i32_16x16x64_i8 v[108:111], v[188:191], v[244:247], v[108:111]
	s_setprio 0
	s_setprio 1
	v_mfma_i32_16x16x64_i8 v[164:167], v[192:195], v[216:219], v[164:167]
	v_mfma_i32_16x16x64_i8 v[156:159], v[204:207], v[216:219], v[156:159]
	v_mfma_i32_16x16x64_i8 v[148:151], v[192:195], v[224:227], v[148:151]
	v_mfma_i32_16x16x64_i8 v[140:143], v[204:207], v[224:227], v[140:143]
	v_mfma_i32_16x16x64_i8 v[132:135], v[192:195], v[232:235], v[132:135]
	v_mfma_i32_16x16x64_i8 v[124:127], v[204:207], v[232:235], v[124:127]
	v_mfma_i32_16x16x64_i8 v[116:119], v[192:195], v[240:243], v[116:119]
	v_mfma_i32_16x16x64_i8 v[104:107], v[204:207], v[240:243], v[104:107]
	v_mfma_i32_16x16x64_i8 v[164:167], v[200:203], v[220:223], v[164:167]
	v_mfma_i32_16x16x64_i8 v[156:159], v[210:213], v[220:223], v[156:159]
	v_mfma_i32_16x16x64_i8 v[148:151], v[200:203], v[228:231], v[148:151]
	v_mfma_i32_16x16x64_i8 v[140:143], v[210:213], v[228:231], v[140:143]
	v_mfma_i32_16x16x64_i8 v[132:135], v[200:203], v[236:239], v[132:135]
	v_mfma_i32_16x16x64_i8 v[124:127], v[210:213], v[236:239], v[124:127]
	v_mfma_i32_16x16x64_i8 v[116:119], v[200:203], v[244:247], v[116:119]
	v_mfma_i32_16x16x64_i8 v[104:107], v[210:213], v[244:247], v[104:107]
	s_setprio 0
	s_barrier
	s_add_i32 s34, s48, s0
	s_mov_b32 m0, s34
	ds_read_b128 v[216:219], v197 offset:16384
	ds_read_b128 v[220:223], v197 offset:17408
	ds_read_b128 v[224:227], v197 offset:18432
	ds_read_b128 v[228:231], v197 offset:19456
	ds_read_b128 v[232:235], v197 offset:20480
	ds_read_b128 v[236:239], v197 offset:21504
	ds_read_b128 v[240:243], v197 offset:22528
	ds_read_b128 v[244:247], v197 offset:23552
	global_load_lds_dwordx4 v176, s[64:65]
	s_add_i32 m0, s34, 0x2000
	s_add_u32 s34, s64, 0x4000
	s_addc_u32 s35, s65, 0
	s_add_i32 s48, s49, s0
	global_load_lds_dwordx4 v180, s[64:65]
	s_mov_b32 m0, s48
	s_nop 0
	global_load_lds_dwordx4 v176, s[34:35]
	s_add_i32 m0, s48, 0x2000
	s_nop 0
	global_load_lds_dwordx4 v180, s[34:35]
	s_mov_b32 m0, s29
	s_nop 0
	global_load_lds_dwordx4 v178, s[66:67]
	s_mov_b32 m0, s45
	s_nop 0
	global_load_lds_dwordx4 v182, s[66:67]
	s_waitcnt vmcnt(8)
	s_waitcnt lgkmcnt(0)
	s_barrier
	s_setprio 1
	s_waitcnt lgkmcnt(0)
	v_mfma_i32_16x16x64_i8 v[96:99], v[100:103], v[216:219], v[96:99]
	v_mfma_i32_16x16x64_i8 v[88:91], v[172:175], v[216:219], v[88:91]
	v_mfma_i32_16x16x64_i8 v[80:83], v[100:103], v[224:227], v[80:83]
	v_mfma_i32_16x16x64_i8 v[72:75], v[172:175], v[224:227], v[72:75]
	v_mfma_i32_16x16x64_i8 v[64:67], v[100:103], v[232:235], v[64:67]
	v_mfma_i32_16x16x64_i8 v[56:59], v[172:175], v[232:235], v[56:59]
	v_mfma_i32_16x16x64_i8 v[48:51], v[100:103], v[240:243], v[48:51]
	v_mfma_i32_16x16x64_i8 v[40:43], v[172:175], v[240:243], v[40:43]
	v_mfma_i32_16x16x64_i8 v[96:99], v[112:115], v[220:223], v[96:99]
	v_mfma_i32_16x16x64_i8 v[88:91], v[188:191], v[220:223], v[88:91]
	v_mfma_i32_16x16x64_i8 v[80:83], v[112:115], v[228:231], v[80:83]
	v_mfma_i32_16x16x64_i8 v[72:75], v[188:191], v[228:231], v[72:75]
	v_mfma_i32_16x16x64_i8 v[64:67], v[112:115], v[236:239], v[64:67]
	v_mfma_i32_16x16x64_i8 v[56:59], v[188:191], v[236:239], v[56:59]
	v_mfma_i32_16x16x64_i8 v[48:51], v[112:115], v[244:247], v[48:51]
	v_mfma_i32_16x16x64_i8 v[40:43], v[188:191], v[244:247], v[40:43]
	s_setprio 0
	s_setprio 1
	v_mfma_i32_16x16x64_i8 v[92:95], v[192:195], v[216:219], v[92:95]
	v_mfma_i32_16x16x64_i8 v[84:87], v[204:207], v[216:219], v[84:87]
	v_mfma_i32_16x16x64_i8 v[76:79], v[192:195], v[224:227], v[76:79]
	v_mfma_i32_16x16x64_i8 v[68:71], v[204:207], v[224:227], v[68:71]
	v_mfma_i32_16x16x64_i8 v[60:63], v[192:195], v[232:235], v[60:63]
	v_mfma_i32_16x16x64_i8 v[52:55], v[204:207], v[232:235], v[52:55]
	v_mfma_i32_16x16x64_i8 v[44:47], v[192:195], v[240:243], v[44:47]
	v_mfma_i32_16x16x64_i8 v[36:39], v[204:207], v[240:243], v[36:39]
	v_mfma_i32_16x16x64_i8 v[92:95], v[200:203], v[220:223], v[92:95]
	v_mfma_i32_16x16x64_i8 v[84:87], v[210:213], v[220:223], v[84:87]
	v_mfma_i32_16x16x64_i8 v[76:79], v[200:203], v[228:231], v[76:79]
	v_mfma_i32_16x16x64_i8 v[68:71], v[210:213], v[228:231], v[68:71]
	v_mfma_i32_16x16x64_i8 v[60:63], v[200:203], v[236:239], v[60:63]
	v_mfma_i32_16x16x64_i8 v[52:55], v[210:213], v[236:239], v[52:55]
	v_mfma_i32_16x16x64_i8 v[44:47], v[200:203], v[244:247], v[44:47]
	v_mfma_i32_16x16x64_i8 v[36:39], v[210:213], v[244:247], v[36:39]
	s_setprio 0
	s_barrier
	s_add_i32 s48, 0, 0x18000
	v_add_u32_e32 v0, s48, v196
	s_add_i32 s49, 0, 0x1c000
	ds_read_b128 v[100:103], v0
	ds_read_b128 v[112:115], v0 offset:1024
	ds_read_b128 v[172:175], v0 offset:2048
	ds_read_b128 v[188:191], v0 offset:3072
	v_add_u32_e32 v0, s49, v196
	ds_read_b128 v[192:195], v0
	ds_read_b128 v[200:203], v0 offset:1024
	ds_read_b128 v[204:207], v0 offset:2048
	ds_read_b128 v[210:213], v0 offset:3072
	s_add_u32 s34, s66, 0x100000
	s_addc_u32 s35, s67, 0
	s_mov_b32 m0, s82
	ds_read_b128 v[216:219], v197 offset:32768
	ds_read_b128 v[220:223], v197 offset:33792
	ds_read_b128 v[224:227], v197 offset:34816
	ds_read_b128 v[228:231], v197 offset:35840
	ds_read_b128 v[232:235], v197 offset:36864
	ds_read_b128 v[236:239], v197 offset:37888
	ds_read_b128 v[240:243], v197 offset:38912
	ds_read_b128 v[244:247], v197 offset:39936
	global_load_lds_dwordx4 v178, s[34:35]
	s_mov_b32 m0, s90
	s_nop 0
	global_load_lds_dwordx4 v182, s[34:35]
	s_waitcnt vmcnt(8)
	s_waitcnt lgkmcnt(0)
	s_barrier
	s_setprio 1
	s_waitcnt lgkmcnt(0)
	v_mfma_i32_16x16x64_i8 v[168:171], v[100:103], v[216:219], v[168:171]
	v_mfma_i32_16x16x64_i8 v[160:163], v[172:175], v[216:219], v[160:163]
	v_mfma_i32_16x16x64_i8 v[152:155], v[100:103], v[224:227], v[152:155]
	v_mfma_i32_16x16x64_i8 v[144:147], v[172:175], v[224:227], v[144:147]
	v_mfma_i32_16x16x64_i8 v[136:139], v[100:103], v[232:235], v[136:139]
	v_mfma_i32_16x16x64_i8 v[128:131], v[172:175], v[232:235], v[128:131]
	v_mfma_i32_16x16x64_i8 v[120:123], v[100:103], v[240:243], v[120:123]
	v_mfma_i32_16x16x64_i8 v[108:111], v[172:175], v[240:243], v[108:111]
	v_mfma_i32_16x16x64_i8 v[168:171], v[112:115], v[220:223], v[168:171]
	v_mfma_i32_16x16x64_i8 v[160:163], v[188:191], v[220:223], v[160:163]
	v_mfma_i32_16x16x64_i8 v[152:155], v[112:115], v[228:231], v[152:155]
	v_mfma_i32_16x16x64_i8 v[144:147], v[188:191], v[228:231], v[144:147]
	v_mfma_i32_16x16x64_i8 v[136:139], v[112:115], v[236:239], v[136:139]
	v_mfma_i32_16x16x64_i8 v[128:131], v[188:191], v[236:239], v[128:131]
	v_mfma_i32_16x16x64_i8 v[120:123], v[112:115], v[244:247], v[120:123]
	v_mfma_i32_16x16x64_i8 v[108:111], v[188:191], v[244:247], v[108:111]
	s_setprio 0
	s_setprio 1
	v_mfma_i32_16x16x64_i8 v[164:167], v[192:195], v[216:219], v[164:167]
	v_mfma_i32_16x16x64_i8 v[156:159], v[204:207], v[216:219], v[156:159]
	v_mfma_i32_16x16x64_i8 v[148:151], v[192:195], v[224:227], v[148:151]
	v_mfma_i32_16x16x64_i8 v[140:143], v[204:207], v[224:227], v[140:143]
	v_mfma_i32_16x16x64_i8 v[132:135], v[192:195], v[232:235], v[132:135]
	v_mfma_i32_16x16x64_i8 v[124:127], v[204:207], v[232:235], v[124:127]
	v_mfma_i32_16x16x64_i8 v[116:119], v[192:195], v[240:243], v[116:119]
	v_mfma_i32_16x16x64_i8 v[104:107], v[204:207], v[240:243], v[104:107]
	v_mfma_i32_16x16x64_i8 v[164:167], v[200:203], v[220:223], v[164:167]
	v_mfma_i32_16x16x64_i8 v[156:159], v[210:213], v[220:223], v[156:159]
	v_mfma_i32_16x16x64_i8 v[148:151], v[200:203], v[228:231], v[148:151]
	v_mfma_i32_16x16x64_i8 v[140:143], v[210:213], v[228:231], v[140:143]
	v_mfma_i32_16x16x64_i8 v[132:135], v[200:203], v[236:239], v[132:135]
	v_mfma_i32_16x16x64_i8 v[124:127], v[210:213], v[236:239], v[124:127]
	v_mfma_i32_16x16x64_i8 v[116:119], v[200:203], v[244:247], v[116:119]
	v_mfma_i32_16x16x64_i8 v[104:107], v[210:213], v[244:247], v[104:107]
	s_setprio 0
	s_barrier
	s_add_u32 s34, s64, 0x8000
	s_addc_u32 s35, s65, 0
	s_add_i32 s48, s48, s0
	s_mov_b32 m0, s48
	ds_read_b128 v[216:219], v197 offset:49152
	ds_read_b128 v[220:223], v197 offset:50176
	ds_read_b128 v[224:227], v197 offset:51200
	ds_read_b128 v[228:231], v197 offset:52224
	ds_read_b128 v[232:235], v197 offset:53248
	ds_read_b128 v[236:239], v197 offset:54272
	ds_read_b128 v[240:243], v197 offset:55296
	ds_read_b128 v[244:247], v197 offset:56320
	global_load_lds_dwordx4 v176, s[34:35]
	s_add_i32 m0, s48, 0x2000
	v_lshl_add_u64 v[252:253], s[34:35], 0, v[180:181]
	s_add_u32 s34, s64, 0xc000
	s_addc_u32 s35, s65, 0
	s_add_i32 s48, s49, s0
	global_load_lds_dwordx4 v[252:253], off
	s_mov_b32 m0, s48
	s_nop 0
	global_load_lds_dwordx4 v176, s[34:35]
	s_add_i32 m0, s48, 0x2000
	s_nop 0
	global_load_lds_dwordx4 v180, s[34:35]
	s_mov_b32 m0, s91
	s_nop 0
	s_add_u32 s100, s66, s92
	s_addc_u32 s101, s67, s93
	global_load_lds_dwordx4 v178, s[100:101]
	s_mov_b32 m0, s30
	s_nop 0
	s_add_u32 s100, s66, s92
	s_addc_u32 s101, s67, s93
	global_load_lds_dwordx4 v182, s[100:101]
	s_waitcnt vmcnt(8)
	s_waitcnt lgkmcnt(0)
	s_barrier
	s_setprio 1
	s_waitcnt lgkmcnt(0)
	v_mfma_i32_16x16x64_i8 v[96:99], v[100:103], v[216:219], v[96:99]
	v_mfma_i32_16x16x64_i8 v[88:91], v[172:175], v[216:219], v[88:91]
	v_mfma_i32_16x16x64_i8 v[80:83], v[100:103], v[224:227], v[80:83]
	v_mfma_i32_16x16x64_i8 v[72:75], v[172:175], v[224:227], v[72:75]
	v_mfma_i32_16x16x64_i8 v[64:67], v[100:103], v[232:235], v[64:67]
	v_mfma_i32_16x16x64_i8 v[56:59], v[172:175], v[232:235], v[56:59]
	v_mfma_i32_16x16x64_i8 v[48:51], v[100:103], v[240:243], v[48:51]
	v_mfma_i32_16x16x64_i8 v[40:43], v[172:175], v[240:243], v[40:43]
	v_mfma_i32_16x16x64_i8 v[96:99], v[112:115], v[220:223], v[96:99]
	v_mfma_i32_16x16x64_i8 v[88:91], v[188:191], v[220:223], v[88:91]
	v_mfma_i32_16x16x64_i8 v[80:83], v[112:115], v[228:231], v[80:83]
	v_mfma_i32_16x16x64_i8 v[72:75], v[188:191], v[228:231], v[72:75]
	v_mfma_i32_16x16x64_i8 v[64:67], v[112:115], v[236:239], v[64:67]
	v_mfma_i32_16x16x64_i8 v[56:59], v[188:191], v[236:239], v[56:59]
	v_mfma_i32_16x16x64_i8 v[48:51], v[112:115], v[244:247], v[48:51]
	v_mfma_i32_16x16x64_i8 v[40:43], v[188:191], v[244:247], v[40:43]
	s_setprio 0
	s_setprio 1
	v_mfma_i32_16x16x64_i8 v[92:95], v[192:195], v[216:219], v[92:95]
	v_mfma_i32_16x16x64_i8 v[84:87], v[204:207], v[216:219], v[84:87]
	v_mfma_i32_16x16x64_i8 v[76:79], v[192:195], v[224:227], v[76:79]
	v_mfma_i32_16x16x64_i8 v[68:71], v[204:207], v[224:227], v[68:71]
	v_mfma_i32_16x16x64_i8 v[60:63], v[192:195], v[232:235], v[60:63]
	v_mfma_i32_16x16x64_i8 v[52:55], v[204:207], v[232:235], v[52:55]
	v_mfma_i32_16x16x64_i8 v[44:47], v[192:195], v[240:243], v[44:47]
	v_mfma_i32_16x16x64_i8 v[36:39], v[204:207], v[240:243], v[36:39]
	v_mfma_i32_16x16x64_i8 v[92:95], v[200:203], v[220:223], v[92:95]
	v_mfma_i32_16x16x64_i8 v[84:87], v[210:213], v[220:223], v[84:87]
	v_mfma_i32_16x16x64_i8 v[76:79], v[200:203], v[228:231], v[76:79]
	v_mfma_i32_16x16x64_i8 v[68:71], v[210:213], v[228:231], v[68:71]
	v_mfma_i32_16x16x64_i8 v[60:63], v[200:203], v[236:239], v[60:63]
	v_mfma_i32_16x16x64_i8 v[52:55], v[210:213], v[236:239], v[52:55]
	v_mfma_i32_16x16x64_i8 v[44:47], v[200:203], v[244:247], v[44:47]
	v_mfma_i32_16x16x64_i8 v[36:39], v[210:213], v[244:247], v[36:39]
	s_setprio 0
	s_barrier
	s_add_i32 s59, s59, 2
	s_add_u32 s28, s28, 0x10000
	s_addc_u32 s58, s58, 0
	s_add_u32 s12, s12, 0x100
	s_addc_u32 s13, s13, 0
	s_cmp_gt_u32 s59, 29
	s_cbranch_scc0 .LBB0_1070
	s_and_b64 vcc, exec, s[46:47]
	s_cbranch_vccz .LBB0_1073
	s_barrier

.LBB0_1261:
	s_add_u32 s42, s22, 0x100
	s_addc_u32 s43, s23, 0
	s_add_i32 s34, 0, 0x10000
	s_cmpk_eq_i32 s60, 0xa8
	s_cselect_b32 s51, s19, s43
	s_cselect_b32 s50, s18, s42
	v_add_u32_e32 v0, s34, v186
	s_cselect_b32 s49, s21, s59
	s_cselect_b32 s48, s20, s58
	s_add_i32 s35, 0, 0x14000
	ds_read_b128 v[132:135], v0
	ds_read_b128 v[136:139], v0 offset:1024
	ds_read_b128 v[140:143], v0 offset:2048
	ds_read_b128 v[144:147], v0 offset:3072
	v_add_u32_e32 v0, s35, v186
	ds_read_b128 v[148:151], v0
	ds_read_b128 v[152:155], v0 offset:1024
	ds_read_b128 v[168:171], v0 offset:2048
	ds_read_b128 v[172:175], v0 offset:3072
	s_add_i32 m0, s29, 0xc000
	ds_read_b128 v[176:179], v187
	ds_read_b128 v[180:183], v187 offset:1024
	ds_read_b128 v[192:195], v187 offset:2048
	ds_read_b128 v[210:213], v187 offset:3072
	ds_read_b128 v[232:235], v187 offset:4096
	ds_read_b128 v[236:239], v187 offset:5120
	ds_read_b128 v[240:243], v187 offset:6144
	ds_read_b128 v[244:247], v187 offset:7168
	global_load_lds_dwordx4 v164, s[22:23]
	s_add_i32 m0, s29, 0xe000
	s_nop 0
	global_load_lds_dwordx4 v166, s[22:23]
	s_waitcnt vmcnt(8)
	s_waitcnt lgkmcnt(0)
	s_barrier
	s_setprio 1
	s_waitcnt lgkmcnt(0)
	v_mfma_f32_16x16x32_bf16 v[128:131], v[132:135], v[176:179], v[128:131]
	v_mfma_f32_16x16x32_bf16 v[124:127], v[140:143], v[176:179], v[124:127]
	v_mfma_f32_16x16x32_bf16 v[112:115], v[132:135], v[192:195], v[112:115]
	v_mfma_f32_16x16x32_bf16 v[108:111], v[140:143], v[192:195], v[108:111]
	v_mfma_f32_16x16x32_bf16 v[96:99], v[132:135], v[232:235], v[96:99]
	v_mfma_f32_16x16x32_bf16 v[92:95], v[140:143], v[232:235], v[92:95]
	v_mfma_f32_16x16x32_bf16 v[80:83], v[132:135], v[240:243], v[80:83]
	v_mfma_f32_16x16x32_bf16 v[76:79], v[140:143], v[240:243], v[76:79]
	v_mfma_f32_16x16x32_bf16 v[128:131], v[136:139], v[180:183], v[128:131]
	v_mfma_f32_16x16x32_bf16 v[124:127], v[144:147], v[180:183], v[124:127]
	v_mfma_f32_16x16x32_bf16 v[112:115], v[136:139], v[210:213], v[112:115]
	v_mfma_f32_16x16x32_bf16 v[108:111], v[144:147], v[210:213], v[108:111]
	v_mfma_f32_16x16x32_bf16 v[96:99], v[136:139], v[236:239], v[96:99]
	v_mfma_f32_16x16x32_bf16 v[92:95], v[144:147], v[236:239], v[92:95]
	v_mfma_f32_16x16x32_bf16 v[80:83], v[136:139], v[244:247], v[80:83]
	v_mfma_f32_16x16x32_bf16 v[76:79], v[144:147], v[244:247], v[76:79]
	s_setprio 0
	s_setprio 1
	v_mfma_f32_16x16x32_bf16 v[120:123], v[148:151], v[176:179], v[120:123]
	v_mfma_f32_16x16x32_bf16 v[116:119], v[168:171], v[176:179], v[116:119]
	v_mfma_f32_16x16x32_bf16 v[104:107], v[148:151], v[192:195], v[104:107]
	v_mfma_f32_16x16x32_bf16 v[100:103], v[168:171], v[192:195], v[100:103]
	v_mfma_f32_16x16x32_bf16 v[88:91], v[148:151], v[232:235], v[88:91]
	v_mfma_f32_16x16x32_bf16 v[84:87], v[168:171], v[232:235], v[84:87]
	v_mfma_f32_16x16x32_bf16 v[72:75], v[148:151], v[240:243], v[72:75]
	v_mfma_f32_16x16x32_bf16 v[68:71], v[168:171], v[240:243], v[68:71]
	v_mfma_f32_16x16x32_bf16 v[120:123], v[152:155], v[180:183], v[120:123]
	v_mfma_f32_16x16x32_bf16 v[116:119], v[172:175], v[180:183], v[116:119]
	v_mfma_f32_16x16x32_bf16 v[104:107], v[152:155], v[210:213], v[104:107]
	v_mfma_f32_16x16x32_bf16 v[100:103], v[172:175], v[210:213], v[100:103]
	v_mfma_f32_16x16x32_bf16 v[88:91], v[152:155], v[236:239], v[88:91]
	v_mfma_f32_16x16x32_bf16 v[84:87], v[172:175], v[236:239], v[84:87]
	v_mfma_f32_16x16x32_bf16 v[72:75], v[152:155], v[244:247], v[72:75]
	v_mfma_f32_16x16x32_bf16 v[68:71], v[172:175], v[244:247], v[68:71]
	s_setprio 0
	s_barrier
	s_add_i32 s22, s34, s0
	s_mov_b32 m0, s22
	ds_read_b128 v[176:179], v187 offset:16384
	ds_read_b128 v[180:183], v187 offset:17408
	ds_read_b128 v[192:195], v187 offset:18432
	ds_read_b128 v[210:213], v187 offset:19456
	ds_read_b128 v[232:235], v187 offset:20480
	ds_read_b128 v[236:239], v187 offset:21504
	ds_read_b128 v[240:243], v187 offset:22528
	ds_read_b128 v[244:247], v187 offset:23552
	global_load_lds_dwordx4 v156, s[48:49]
	s_add_i32 m0, s22, 0x2000
	s_add_u32 s22, s48, 0x4000
	s_addc_u32 s23, s49, 0
	s_add_i32 s34, s35, s0
	global_load_lds_dwordx4 v160, s[48:49]
	s_mov_b32 m0, s34
	s_nop 0
	global_load_lds_dwordx4 v156, s[22:23]
	s_add_i32 m0, s34, 0x2000
	s_nop 0
	global_load_lds_dwordx4 v160, s[22:23]
	s_mov_b32 m0, s29
	s_nop 0
	global_load_lds_dwordx4 v158, s[50:51]
	s_mov_b32 m0, s45
	s_nop 0
	global_load_lds_dwordx4 v162, s[50:51]
	s_waitcnt vmcnt(8)
	s_waitcnt lgkmcnt(0)
	s_barrier
	s_setprio 1
	s_waitcnt lgkmcnt(0)
	v_mfma_f32_16x16x32_bf16 v[64:67], v[132:135], v[176:179], v[64:67]
	v_mfma_f32_16x16x32_bf16 v[60:63], v[140:143], v[176:179], v[60:63]
	v_mfma_f32_16x16x32_bf16 v[48:51], v[132:135], v[192:195], v[48:51]
	v_mfma_f32_16x16x32_bf16 v[44:47], v[140:143], v[192:195], v[44:47]
	v_mfma_f32_16x16x32_bf16 v[30:33], v[132:135], v[232:235], v[30:33]
	v_mfma_f32_16x16x32_bf16 v[26:29], v[140:143], v[232:235], v[26:29]
	v_mfma_f32_16x16x32_bf16 v[14:17], v[132:135], v[240:243], v[14:17]
	v_mfma_f32_16x16x32_bf16 v[10:13], v[140:143], v[240:243], v[10:13]
	v_mfma_f32_16x16x32_bf16 v[64:67], v[136:139], v[180:183], v[64:67]
	v_mfma_f32_16x16x32_bf16 v[60:63], v[144:147], v[180:183], v[60:63]
	v_mfma_f32_16x16x32_bf16 v[48:51], v[136:139], v[210:213], v[48:51]
	v_mfma_f32_16x16x32_bf16 v[44:47], v[144:147], v[210:213], v[44:47]
	v_mfma_f32_16x16x32_bf16 v[30:33], v[136:139], v[236:239], v[30:33]
	v_mfma_f32_16x16x32_bf16 v[26:29], v[144:147], v[236:239], v[26:29]
	v_mfma_f32_16x16x32_bf16 v[14:17], v[136:139], v[244:247], v[14:17]
	v_mfma_f32_16x16x32_bf16 v[10:13], v[144:147], v[244:247], v[10:13]
	s_setprio 0
	s_setprio 1
	v_mfma_f32_16x16x32_bf16 v[56:59], v[148:151], v[176:179], v[56:59]
	v_mfma_f32_16x16x32_bf16 v[52:55], v[168:171], v[176:179], v[52:55]
	v_mfma_f32_16x16x32_bf16 v[40:43], v[148:151], v[192:195], v[40:43]
	v_mfma_f32_16x16x32_bf16 v[36:39], v[168:171], v[192:195], v[36:39]
	v_mfma_f32_16x16x32_bf16 v[22:25], v[148:151], v[232:235], v[22:25]
	v_mfma_f32_16x16x32_bf16 v[18:21], v[168:171], v[232:235], v[18:21]
	v_mfma_f32_16x16x32_bf16 v[6:9], v[148:151], v[240:243], v[6:9]
	v_mfma_f32_16x16x32_bf16 v[2:5], v[168:171], v[240:243], v[2:5]
	v_mfma_f32_16x16x32_bf16 v[56:59], v[152:155], v[180:183], v[56:59]
	v_mfma_f32_16x16x32_bf16 v[52:55], v[172:175], v[180:183], v[52:55]
	v_mfma_f32_16x16x32_bf16 v[40:43], v[152:155], v[210:213], v[40:43]
	v_mfma_f32_16x16x32_bf16 v[36:39], v[172:175], v[210:213], v[36:39]
	v_mfma_f32_16x16x32_bf16 v[22:25], v[152:155], v[236:239], v[22:25]
	v_mfma_f32_16x16x32_bf16 v[18:21], v[172:175], v[236:239], v[18:21]
	v_mfma_f32_16x16x32_bf16 v[6:9], v[152:155], v[244:247], v[6:9]
	v_mfma_f32_16x16x32_bf16 v[2:5], v[172:175], v[244:247], v[2:5]
	s_setprio 0
	s_barrier
	s_add_i32 s34, 0, 0x18000
	v_add_u32_e32 v0, s34, v186
	s_add_i32 s35, 0, 0x1c000
	ds_read_b128 v[132:135], v0
	ds_read_b128 v[136:139], v0 offset:1024
	ds_read_b128 v[140:143], v0 offset:2048
	ds_read_b128 v[144:147], v0 offset:3072
	v_add_u32_e32 v0, s35, v186
	ds_read_b128 v[148:151], v0
	ds_read_b128 v[152:155], v0 offset:1024
	ds_read_b128 v[168:171], v0 offset:2048
	ds_read_b128 v[172:175], v0 offset:3072
	s_add_u32 s22, s50, 0x2b0000
	s_addc_u32 s23, s51, 0
	s_mov_b32 m0, s82
	ds_read_b128 v[176:179], v187 offset:32768
	ds_read_b128 v[180:183], v187 offset:33792
	ds_read_b128 v[192:195], v187 offset:34816
	ds_read_b128 v[210:213], v187 offset:35840
	ds_read_b128 v[232:235], v187 offset:36864
	ds_read_b128 v[236:239], v187 offset:37888
	ds_read_b128 v[240:243], v187 offset:38912
	ds_read_b128 v[244:247], v187 offset:39936
	global_load_lds_dwordx4 v158, s[22:23]
	s_mov_b32 m0, s90
	s_nop 0
	global_load_lds_dwordx4 v162, s[22:23]
	s_waitcnt vmcnt(8)
	s_waitcnt lgkmcnt(0)
	s_barrier
	s_setprio 1
	s_waitcnt lgkmcnt(0)
	v_mfma_f32_16x16x32_bf16 v[128:131], v[132:135], v[176:179], v[128:131]
	v_mfma_f32_16x16x32_bf16 v[124:127], v[140:143], v[176:179], v[124:127]
	v_mfma_f32_16x16x32_bf16 v[112:115], v[132:135], v[192:195], v[112:115]
	v_mfma_f32_16x16x32_bf16 v[108:111], v[140:143], v[192:195], v[108:111]
	v_mfma_f32_16x16x32_bf16 v[96:99], v[132:135], v[232:235], v[96:99]
	v_mfma_f32_16x16x32_bf16 v[92:95], v[140:143], v[232:235], v[92:95]
	v_mfma_f32_16x16x32_bf16 v[80:83], v[132:135], v[240:243], v[80:83]
	v_mfma_f32_16x16x32_bf16 v[76:79], v[140:143], v[240:243], v[76:79]
	v_mfma_f32_16x16x32_bf16 v[128:131], v[136:139], v[180:183], v[128:131]
	v_mfma_f32_16x16x32_bf16 v[124:127], v[144:147], v[180:183], v[124:127]
	v_mfma_f32_16x16x32_bf16 v[112:115], v[136:139], v[210:213], v[112:115]
	v_mfma_f32_16x16x32_bf16 v[108:111], v[144:147], v[210:213], v[108:111]
	v_mfma_f32_16x16x32_bf16 v[96:99], v[136:139], v[236:239], v[96:99]
	v_mfma_f32_16x16x32_bf16 v[92:95], v[144:147], v[236:239], v[92:95]
	v_mfma_f32_16x16x32_bf16 v[80:83], v[136:139], v[244:247], v[80:83]
	v_mfma_f32_16x16x32_bf16 v[76:79], v[144:147], v[244:247], v[76:79]
	s_setprio 0
	s_setprio 1
	v_mfma_f32_16x16x32_bf16 v[120:123], v[148:151], v[176:179], v[120:123]
	v_mfma_f32_16x16x32_bf16 v[116:119], v[168:171], v[176:179], v[116:119]
	v_mfma_f32_16x16x32_bf16 v[104:107], v[148:151], v[192:195], v[104:107]
	v_mfma_f32_16x16x32_bf16 v[100:103], v[168:171], v[192:195], v[100:103]
	v_mfma_f32_16x16x32_bf16 v[88:91], v[148:151], v[232:235], v[88:91]
	v_mfma_f32_16x16x32_bf16 v[84:87], v[168:171], v[232:235], v[84:87]
	v_mfma_f32_16x16x32_bf16 v[72:75], v[148:151], v[240:243], v[72:75]
	v_mfma_f32_16x16x32_bf16 v[68:71], v[168:171], v[240:243], v[68:71]
	v_mfma_f32_16x16x32_bf16 v[120:123], v[152:155], v[180:183], v[120:123]
	v_mfma_f32_16x16x32_bf16 v[116:119], v[172:175], v[180:183], v[116:119]
	v_mfma_f32_16x16x32_bf16 v[104:107], v[152:155], v[210:213], v[104:107]
	v_mfma_f32_16x16x32_bf16 v[100:103], v[172:175], v[210:213], v[100:103]
	v_mfma_f32_16x16x32_bf16 v[88:91], v[152:155], v[236:239], v[88:91]
	v_mfma_f32_16x16x32_bf16 v[84:87], v[172:175], v[236:239], v[84:87]
	v_mfma_f32_16x16x32_bf16 v[72:75], v[152:155], v[244:247], v[72:75]
	v_mfma_f32_16x16x32_bf16 v[68:71], v[172:175], v[244:247], v[68:71]
	s_setprio 0
	s_barrier
	s_add_u32 s22, s48, 0x8000
	s_addc_u32 s23, s49, 0
	s_add_i32 s34, s34, s0
	s_mov_b32 m0, s34
	ds_read_b128 v[176:179], v187 offset:49152
	ds_read_b128 v[180:183], v187 offset:50176
	ds_read_b128 v[192:195], v187 offset:51200
	ds_read_b128 v[210:213], v187 offset:52224
	ds_read_b128 v[232:235], v187 offset:53248
	ds_read_b128 v[236:239], v187 offset:54272
	ds_read_b128 v[240:243], v187 offset:55296
	ds_read_b128 v[244:247], v187 offset:56320
	global_load_lds_dwordx4 v156, s[22:23]
	s_add_i32 m0, s34, 0x2000
	v_lshl_add_u64 v[250:251], s[22:23], 0, v[160:161]
	s_add_u32 s22, s48, 0xc000
	s_addc_u32 s23, s49, 0
	s_add_i32 s34, s35, s0
	global_load_lds_dwordx4 v[250:251], off
	s_mov_b32 m0, s34
	s_nop 0
	global_load_lds_dwordx4 v156, s[22:23]
	s_add_i32 m0, s34, 0x2000
	s_nop 0
	global_load_lds_dwordx4 v160, s[22:23]
	s_mov_b32 m0, s91
	s_nop 0
	s_add_u32 s100, s50, s92
	s_addc_u32 s101, s51, s93
	global_load_lds_dwordx4 v158, s[100:101]
	s_mov_b32 m0, s30
	s_nop 0
	s_add_u32 s100, s50, s92
	s_addc_u32 s101, s51, s93
	global_load_lds_dwordx4 v162, s[100:101]
	s_waitcnt vmcnt(8)
	s_waitcnt lgkmcnt(0)
	s_barrier
	s_setprio 1
	s_waitcnt lgkmcnt(0)
	v_mfma_f32_16x16x32_bf16 v[64:67], v[132:135], v[176:179], v[64:67]
	v_mfma_f32_16x16x32_bf16 v[60:63], v[140:143], v[176:179], v[60:63]
	v_mfma_f32_16x16x32_bf16 v[48:51], v[132:135], v[192:195], v[48:51]
	v_mfma_f32_16x16x32_bf16 v[44:47], v[140:143], v[192:195], v[44:47]
	v_mfma_f32_16x16x32_bf16 v[30:33], v[132:135], v[232:235], v[30:33]
	v_mfma_f32_16x16x32_bf16 v[26:29], v[140:143], v[232:235], v[26:29]
	v_mfma_f32_16x16x32_bf16 v[14:17], v[132:135], v[240:243], v[14:17]
	v_mfma_f32_16x16x32_bf16 v[10:13], v[140:143], v[240:243], v[10:13]
	v_mfma_f32_16x16x32_bf16 v[64:67], v[136:139], v[180:183], v[64:67]
	v_mfma_f32_16x16x32_bf16 v[60:63], v[144:147], v[180:183], v[60:63]
	v_mfma_f32_16x16x32_bf16 v[48:51], v[136:139], v[210:213], v[48:51]
	v_mfma_f32_16x16x32_bf16 v[44:47], v[144:147], v[210:213], v[44:47]
	v_mfma_f32_16x16x32_bf16 v[30:33], v[136:139], v[236:239], v[30:33]
	v_mfma_f32_16x16x32_bf16 v[26:29], v[144:147], v[236:239], v[26:29]
	v_mfma_f32_16x16x32_bf16 v[14:17], v[136:139], v[244:247], v[14:17]
	v_mfma_f32_16x16x32_bf16 v[10:13], v[144:147], v[244:247], v[10:13]
	s_setprio 0
	s_setprio 1
	v_mfma_f32_16x16x32_bf16 v[56:59], v[148:151], v[176:179], v[56:59]
	v_mfma_f32_16x16x32_bf16 v[52:55], v[168:171], v[176:179], v[52:55]
	v_mfma_f32_16x16x32_bf16 v[40:43], v[148:151], v[192:195], v[40:43]
	v_mfma_f32_16x16x32_bf16 v[36:39], v[168:171], v[192:195], v[36:39]
	v_mfma_f32_16x16x32_bf16 v[22:25], v[148:151], v[232:235], v[22:25]
	v_mfma_f32_16x16x32_bf16 v[18:21], v[168:171], v[232:235], v[18:21]
	v_mfma_f32_16x16x32_bf16 v[6:9], v[148:151], v[240:243], v[6:9]
	v_mfma_f32_16x16x32_bf16 v[2:5], v[168:171], v[240:243], v[2:5]
	v_mfma_f32_16x16x32_bf16 v[56:59], v[152:155], v[180:183], v[56:59]
	v_mfma_f32_16x16x32_bf16 v[52:55], v[172:175], v[180:183], v[52:55]
	v_mfma_f32_16x16x32_bf16 v[40:43], v[152:155], v[210:213], v[40:43]
	v_mfma_f32_16x16x32_bf16 v[36:39], v[172:175], v[210:213], v[36:39]
	v_mfma_f32_16x16x32_bf16 v[22:25], v[152:155], v[236:239], v[22:25]
	v_mfma_f32_16x16x32_bf16 v[18:21], v[172:175], v[236:239], v[18:21]
	v_mfma_f32_16x16x32_bf16 v[6:9], v[152:155], v[244:247], v[6:9]
	v_mfma_f32_16x16x32_bf16 v[2:5], v[172:175], v[244:247], v[2:5]
	s_setprio 0
	s_barrier
	s_add_i32 s60, s60, 2
	s_add_u32 s58, s58, 0x10000
	s_addc_u32 s59, s59, 0
	s_cmpk_gt_u32 s60, 0xa9
	s_mov_b64 s[22:23], s[42:43]
	s_cbranch_scc0 .LBB0_1261
	s_and_b64 vcc, exec, s[46:47]
	s_cbranch_vccz .LBB0_1264
	s_barrier

	.amdhsa_kernel _Z10fwd_kernel4Args
		.amdhsa_group_segment_fixed_size 0
		.amdhsa_private_segment_fixed_size 0
		.amdhsa_kernarg_size 376
		.amdhsa_user_sgpr_count 2
		.amdhsa_user_sgpr_dispatch_ptr 0
		.amdhsa_user_sgpr_queue_ptr 0
		.amdhsa_user_sgpr_kernarg_segment_ptr 1
		.amdhsa_user_sgpr_dispatch_id 0
		.amdhsa_user_sgpr_kernarg_preload_length 0
		.amdhsa_user_sgpr_kernarg_preload_offset 0
		.amdhsa_user_sgpr_private_segment_size 0
		.amdhsa_uses_dynamic_stack 0
		.amdhsa_enable_private_segment 0
		.amdhsa_system_sgpr_workgroup_id_x 1
		.amdhsa_system_sgpr_workgroup_id_y 0
		.amdhsa_system_sgpr_workgroup_id_z 0
		.amdhsa_system_sgpr_workgroup_info 0
		.amdhsa_system_vgpr_workitem_id 0
		.amdhsa_next_free_vgpr 256
		.amdhsa_next_free_sgpr 102
		.amdhsa_accum_offset 256
		.amdhsa_reserve_vcc 1
		.amdhsa_float_round_mode_32 0
		.amdhsa_float_round_mode_16_64 0
		.amdhsa_float_denorm_mode_32 3
		.amdhsa_float_denorm_mode_16_64 3
		.amdhsa_dx10_clamp 1
		.amdhsa_ieee_mode 1
		.amdhsa_fp16_overflow 0
		.amdhsa_tg_split 0
		.amdhsa_exception_fp_ieee_invalid_op 0
		.amdhsa_exception_fp_denorm_src 0
		.amdhsa_exception_fp_ieee_div_zero 0
		.amdhsa_exception_fp_ieee_overflow 0
		.amdhsa_exception_fp_ieee_underflow 0
		.amdhsa_exception_fp_ieee_inexact 0
		.amdhsa_exception_int_div_zero 0
	.end_amdhsa_kernel

amdhsa.kernels:
  - .agpr_count:     0
    .args:
      - .offset:         0
        .size:           120
        .value_kind:     by_value
      - .offset:         120
        .size:           4
        .value_kind:     hidden_block_count_x
      - .offset:         124
        .size:           4
        .value_kind:     hidden_block_count_y
      - .offset:         128
        .size:           4
        .value_kind:     hidden_block_count_z
      - .offset:         132
        .size:           2
        .value_kind:     hidden_group_size_x
      - .offset:         134
        .size:           2
        .value_kind:     hidden_group_size_y
      - .offset:         136
        .size:           2
        .value_kind:     hidden_group_size_z
      - .offset:         138
        .size:           2
        .value_kind:     hidden_remainder_x
      - .offset:         140
        .size:           2
        .value_kind:     hidden_remainder_y
      - .offset:         142
        .size:           2
        .value_kind:     hidden_remainder_z
      - .offset:         160
        .size:           8
        .value_kind:     hidden_global_offset_x
      - .offset:         168
        .size:           8
        .value_kind:     hidden_global_offset_y
      - .offset:         176
        .size:           8
        .value_kind:     hidden_global_offset_z
      - .offset:         184
        .size:           2
        .value_kind:     hidden_grid_dims
      - .offset:         240
        .size:           4
        .value_kind:     hidden_dynamic_lds_size
    .group_segment_fixed_size: 0
    .kernarg_segment_align: 8
    .kernarg_segment_size: 376
    .language:       OpenCL C
    .language_version:
      - 2
      - 0
    .max_flat_workgroup_size: 512
    .name:           _Z10fwd_kernel4Args
    .private_segment_fixed_size: 0
    .sgpr_count:     108
    .sgpr_spill_count: 122
    .symbol:         _Z10fwd_kernel4Args.kd
    .uniform_work_group_size: 1
    .uses_dynamic_stack: false
    .vgpr_count:     256
    .vgpr_spill_count: 0
    .wavefront_size: 64
